# S5-out epilogue: half-wave exchange (v_permlane32_swap) and 8 dwordx4 stores instead of 16 dwordx2 per unit
# baseline (speedup 1.0000x reference)
; #define GAS __attribute__((address_space(1)))
; #define LAS __attribute__((address_space(3)))
; __device__ __forceinline__ void ph_s5_out(Frame& F) {
;     ...
;         for (int s0 = 0; s0 < 64; s0 += 16) {
;             bf16x8_t bq[16];
; #pragma unroll
;             for (int e = 0; e < 16; ++e) bq[e] = *(const GAS bf16x8_t*)(ub + 512 * (s0 + e));
; #pragma unroll
;             for (int e = 0; e < 16; ++e) { const int sI = s0 + e; const bf16x8_t b = bq[e];
; #pragma unroll
;             for (int i = 0; i < 4; ++i) { const bf16x8_t a = *(const LAS bf16x8_t*)(tl + (16 * i - sI) * 16 * TP_PITCH); acc[i] = __builtin_amdgcn_mfma_f32_32x32x16_bf16(a, b, acc[i], 0, 0, 0); }
;             }
.LBB0_972:
	v_add_co_u32_e32 v210, vcc, 0x2000, v82
	s_nop 1
	v_addc_co_u32_e32 v211, vcc, 0, v83, vcc
	v_add_co_u32_e32 v212, vcc, 0x4000, v82
	s_nop 1
	v_addc_co_u32_e32 v213, vcc, 0, v83, vcc
	ds_read_b128 v[84:87], v68 offset:11520
	ds_read_b128 v[96:99], v68 offset:12288
	s_waitcnt vmcnt(15) lgkmcnt(1)
	v_mfma_f32_32x32x16_bf16 v[50:65], v[84:87], v[142:145], v[50:65]
	ds_read_b128 v[84:87], v68 offset:23808
	ds_read_b128 v[108:111], v68 offset:24576
	s_waitcnt lgkmcnt(1)
	v_mfma_f32_32x32x16_bf16 v[34:49], v[84:87], v[142:145], v[34:49]
	ds_read_b128 v[84:87], v68 offset:36096
	ds_read_b128 v[112:115], v68 offset:36864
	s_waitcnt lgkmcnt(1)
	v_mfma_f32_32x32x16_bf16 v[18:33], v[84:87], v[142:145], v[18:33]
	ds_read_b128 v[84:87], v68 offset:48384
	ds_read_b128 v[116:119], v68
	s_waitcnt lgkmcnt(1)
	v_mfma_f32_32x32x16_bf16 v[2:17], v[84:87], v[142:145], v[2:17]
	global_load_dwordx4 v[142:145], v[82:83], off offset:1024
	ds_read_b128 v[84:87], v68 offset:10752
	ds_read_b128 v[100:103], v68 offset:9984
	s_waitcnt vmcnt(15) lgkmcnt(1)
	v_mfma_f32_32x32x16_bf16 v[50:65], v[84:87], v[146:149], v[50:65]
	ds_read_b128 v[84:87], v68 offset:23040
	ds_read_b128 v[120:123], v68 offset:22272
	s_waitcnt lgkmcnt(1)
	v_mfma_f32_32x32x16_bf16 v[34:49], v[84:87], v[146:149], v[34:49]
	ds_read_b128 v[84:87], v68 offset:35328
	ds_read_b128 v[124:127], v68 offset:34560
	ds_read_b128 v[128:131], v68 offset:46848
	s_waitcnt lgkmcnt(2)
	v_mfma_f32_32x32x16_bf16 v[18:33], v[84:87], v[146:149], v[18:33]
	ds_read_b128 v[84:87], v68 offset:47616
	s_waitcnt lgkmcnt(0)
	v_mfma_f32_32x32x16_bf16 v[2:17], v[84:87], v[146:149], v[2:17]
	global_load_dwordx4 v[146:149], v[82:83], off offset:2048
	s_waitcnt vmcnt(15)
	v_mfma_f32_32x32x16_bf16 v[50:65], v[100:103], v[150:153], v[50:65]
	v_mfma_f32_32x32x16_bf16 v[34:49], v[120:123], v[150:153], v[34:49]
	ds_read_b128 v[100:103], v68 offset:9216
	ds_read_b128 v[120:123], v68 offset:8448
	v_mfma_f32_32x32x16_bf16 v[18:33], v[124:127], v[150:153], v[18:33]
	v_mfma_f32_32x32x16_bf16 v[2:17], v[128:131], v[150:153], v[2:17]
	global_load_dwordx4 v[150:153], v[82:83], off offset:3072
	s_waitcnt vmcnt(15) lgkmcnt(1)
	v_mfma_f32_32x32x16_bf16 v[50:65], v[100:103], v[154:157], v[50:65]
	ds_read_b128 v[100:103], v68 offset:21504
	ds_read_b128 v[128:131], v68 offset:20736
	s_waitcnt lgkmcnt(1)
	v_mfma_f32_32x32x16_bf16 v[34:49], v[100:103], v[154:157], v[34:49]
	ds_read_b128 v[100:103], v68 offset:33792
	ds_read_b128 v[132:135], v68 offset:33024
	s_waitcnt lgkmcnt(1)
	v_mfma_f32_32x32x16_bf16 v[18:33], v[100:103], v[154:157], v[18:33]
	ds_read_b128 v[100:103], v68 offset:46080
	ds_read_b128 v[136:139], v68 offset:45312
	s_waitcnt lgkmcnt(1)
	v_mfma_f32_32x32x16_bf16 v[2:17], v[100:103], v[154:157], v[2:17]
	global_load_dwordx4 v[154:157], v[210:211], off offset:-4096
	s_waitcnt vmcnt(15)
	v_mfma_f32_32x32x16_bf16 v[50:65], v[120:123], v[158:161], v[50:65]
	ds_read_b128 v[100:103], v68 offset:7680
	ds_read_b128 v[120:123], v68 offset:6912
	v_mfma_f32_32x32x16_bf16 v[34:49], v[128:131], v[158:161], v[34:49]
	v_mfma_f32_32x32x16_bf16 v[18:33], v[132:135], v[158:161], v[18:33]
	s_waitcnt lgkmcnt(2)
	v_mfma_f32_32x32x16_bf16 v[2:17], v[136:139], v[158:161], v[2:17]
	global_load_dwordx4 v[158:161], v[210:211], off offset:-3072
	s_waitcnt vmcnt(15) lgkmcnt(1)
	v_mfma_f32_32x32x16_bf16 v[50:65], v[100:103], v[162:165], v[50:65]
	ds_read_b128 v[100:103], v68 offset:19968
	ds_read_b128 v[128:131], v68 offset:19200
	s_waitcnt lgkmcnt(1)
	v_mfma_f32_32x32x16_bf16 v[34:49], v[100:103], v[162:165], v[34:49]
	ds_read_b128 v[100:103], v68 offset:32256
	ds_read_b128 v[132:135], v68 offset:31488
	s_waitcnt lgkmcnt(1)
	v_mfma_f32_32x32x16_bf16 v[18:33], v[100:103], v[162:165], v[18:33]
	ds_read_b128 v[100:103], v68 offset:44544
	ds_read_b128 v[136:139], v68 offset:43776
	s_waitcnt lgkmcnt(1)
	v_mfma_f32_32x32x16_bf16 v[2:17], v[100:103], v[162:165], v[2:17]
	global_load_dwordx4 v[162:165], v[210:211], off offset:-2048
	s_waitcnt vmcnt(15)
	v_mfma_f32_32x32x16_bf16 v[50:65], v[120:123], v[166:169], v[50:65]
	ds_read_b128 v[100:103], v68 offset:6144
	ds_read_b128 v[120:123], v68 offset:5376
	v_mfma_f32_32x32x16_bf16 v[34:49], v[128:131], v[166:169], v[34:49]
	v_mfma_f32_32x32x16_bf16 v[18:33], v[132:135], v[166:169], v[18:33]
	s_waitcnt lgkmcnt(2)
	v_mfma_f32_32x32x16_bf16 v[2:17], v[136:139], v[166:169], v[2:17]
	global_load_dwordx4 v[166:169], v[210:211], off offset:-1024
	s_waitcnt vmcnt(15) lgkmcnt(1)
	v_mfma_f32_32x32x16_bf16 v[50:65], v[100:103], v[170:173], v[50:65]
	ds_read_b128 v[100:103], v68 offset:18432
	ds_read_b128 v[124:127], v68 offset:17664
	s_waitcnt lgkmcnt(1)
	v_mfma_f32_32x32x16_bf16 v[34:49], v[100:103], v[170:173], v[34:49]
	ds_read_b128 v[100:103], v68 offset:30720
	ds_read_b128 v[128:131], v68 offset:29952
	s_waitcnt lgkmcnt(1)
	v_mfma_f32_32x32x16_bf16 v[18:33], v[100:103], v[170:173], v[18:33]
	ds_read_b128 v[100:103], v68 offset:43008
	ds_read_b128 v[132:135], v68 offset:42240
	s_waitcnt lgkmcnt(1)
	v_mfma_f32_32x32x16_bf16 v[2:17], v[100:103], v[170:173], v[2:17]
	global_load_dwordx4 v[170:173], v[210:211], off offset:0
	ds_read_b128 v[84:87], v68 offset:4608
	ds_read_b128 v[100:103], v68 offset:3840
	s_waitcnt vmcnt(15)
	v_mfma_f32_32x32x16_bf16 v[50:65], v[120:123], v[174:177], v[50:65]
	v_mfma_f32_32x32x16_bf16 v[34:49], v[124:127], v[174:177], v[34:49]
	v_mfma_f32_32x32x16_bf16 v[18:33], v[128:131], v[174:177], v[18:33]
	s_waitcnt lgkmcnt(2)
	v_mfma_f32_32x32x16_bf16 v[2:17], v[132:135], v[174:177], v[2:17]
	global_load_dwordx4 v[174:177], v[210:211], off offset:1024
	s_waitcnt vmcnt(15) lgkmcnt(1)
; #define GAS __attribute__((address_space(1)))
; #define LAS __attribute__((address_space(3)))
; __device__ __forceinline__ void ph_s5_out(Frame& F) {
;     ...
;         for (int s0 = 0; s0 < 64; s0 += 16) {
;             bf16x8_t bq[16];
; #pragma unroll
;             for (int e = 0; e < 16; ++e) bq[e] = *(const GAS bf16x8_t*)(ub + 512 * (s0 + e));
; #pragma unroll
;             for (int e = 0; e < 16; ++e) { const int sI = s0 + e; const bf16x8_t b = bq[e];
; #pragma unroll
;             for (int i = 0; i < 4; ++i) { const bf16x8_t a = *(const LAS bf16x8_t*)(tl + (16 * i - sI) * 16 * TP_PITCH); acc[i] = __builtin_amdgcn_mfma_f32_32x32x16_bf16(a, b, acc[i], 0, 0, 0); }
;             }
;         }
;         { const bf16* sb = (const bf16*)(ws + WS_SIN) + (size_t)g * 9 * 16 * 512 + ((size_t)nb * 16 * 64 + lane) * 8;
;           const bf16* wc = (const bf16*)(ws + WS_WC) + (size_t)g * 1024 * 256 + (((size_t)wave * 16) * 64 + lane) * 8;
; #pragma unroll 4
;           for (int kk = 0; kk < 16; ++kk) {
;               const bf16x8_t b = *(const GAS bf16x8_t*)(sb + 512 * kk);
; #pragma unroll
;               for (int i = 0; i < 4; ++i) { const bf16x8_t a = *(const GAS bf16x8_t*)(wc + (size_t)(8 * i) * 16 * 512 + 512 * kk); acc[i] = __builtin_amdgcn_mfma_f32_32x32x16_bf16(a, b, acc[i], 0, 0, 0); }
	v_mfma_f32_32x32x16_bf16 v[50:65], v[84:87], v[178:181], v[50:65]
	ds_read_b128 v[84:87], v68 offset:16896
	ds_read_b128 v[124:127], v68 offset:16128
	s_waitcnt lgkmcnt(1)
	v_mfma_f32_32x32x16_bf16 v[34:49], v[84:87], v[178:181], v[34:49]
	ds_read_b128 v[84:87], v68 offset:29184
	ds_read_b128 v[128:131], v68 offset:28416
	s_waitcnt lgkmcnt(1)
	v_mfma_f32_32x32x16_bf16 v[18:33], v[84:87], v[178:181], v[18:33]
	ds_read_b128 v[84:87], v68 offset:41472
	ds_read_b128 v[132:135], v68 offset:40704
	s_waitcnt lgkmcnt(1)
	v_mfma_f32_32x32x16_bf16 v[2:17], v[84:87], v[178:181], v[2:17]
	global_load_dwordx4 v[178:181], v[210:211], off offset:2048
	s_waitcnt vmcnt(15)
	v_mfma_f32_32x32x16_bf16 v[50:65], v[100:103], v[182:185], v[50:65]
	v_mfma_f32_32x32x16_bf16 v[34:49], v[124:127], v[182:185], v[34:49]
	v_mfma_f32_32x32x16_bf16 v[18:33], v[128:131], v[182:185], v[18:33]
	s_waitcnt lgkmcnt(0)
	v_mfma_f32_32x32x16_bf16 v[2:17], v[132:135], v[182:185], v[2:17]
	global_load_dwordx4 v[182:185], v[210:211], off offset:3072
	ds_read_b128 v[104:107], v68 offset:3072
	ds_read_b128 v[120:123], v68 offset:2304
	s_waitcnt vmcnt(15) lgkmcnt(1)
	v_mfma_f32_32x32x16_bf16 v[50:65], v[104:107], v[190:193], v[50:65]
	ds_read_b128 v[104:107], v68 offset:15360
	ds_read_b128 v[124:127], v68 offset:14592
	s_waitcnt lgkmcnt(1)
	v_mfma_f32_32x32x16_bf16 v[34:49], v[104:107], v[190:193], v[34:49]
	ds_read_b128 v[104:107], v68 offset:27648
	ds_read_b128 v[128:131], v68 offset:26880
	s_waitcnt lgkmcnt(1)
	v_mfma_f32_32x32x16_bf16 v[18:33], v[104:107], v[190:193], v[18:33]
	ds_read_b128 v[104:107], v68 offset:39936
	ds_read_b128 v[132:135], v68 offset:39168
	s_waitcnt lgkmcnt(1)
	v_mfma_f32_32x32x16_bf16 v[2:17], v[104:107], v[190:193], v[2:17]
	global_load_dwordx4 v[190:193], v[212:213], off offset:-4096
	s_waitcnt vmcnt(15)
	v_mfma_f32_32x32x16_bf16 v[50:65], v[120:123], v[194:197], v[50:65]
	v_mfma_f32_32x32x16_bf16 v[34:49], v[124:127], v[194:197], v[34:49]
	v_mfma_f32_32x32x16_bf16 v[18:33], v[128:131], v[194:197], v[18:33]
	s_waitcnt lgkmcnt(0)
	v_mfma_f32_32x32x16_bf16 v[2:17], v[132:135], v[194:197], v[2:17]
	global_load_dwordx4 v[194:197], v[212:213], off offset:-3072
	ds_read_b128 v[100:103], v68 offset:1536
	ds_read_b128 v[120:123], v68 offset:768
	s_waitcnt vmcnt(15) lgkmcnt(1)
	v_mfma_f32_32x32x16_bf16 v[50:65], v[100:103], v[198:201], v[50:65]
	ds_read_b128 v[100:103], v68 offset:13824
	ds_read_b128 v[124:127], v68 offset:13056
	s_waitcnt lgkmcnt(1)
	v_mfma_f32_32x32x16_bf16 v[34:49], v[100:103], v[198:201], v[34:49]
	ds_read_b128 v[100:103], v68 offset:26112
	ds_read_b128 v[128:131], v68 offset:25344
	s_waitcnt lgkmcnt(1)
	v_mfma_f32_32x32x16_bf16 v[18:33], v[100:103], v[198:201], v[18:33]
	ds_read_b128 v[100:103], v68 offset:38400
	ds_read_b128 v[132:135], v68 offset:37632
	v_add_u32_e32 v68, 0xffffd000, v68
	s_waitcnt lgkmcnt(1)
	v_mfma_f32_32x32x16_bf16 v[2:17], v[100:103], v[198:201], v[2:17]
	global_load_dwordx4 v[198:201], v[212:213], off offset:-2048
	s_waitcnt vmcnt(15)
	v_mfma_f32_32x32x16_bf16 v[50:65], v[120:123], v[202:205], v[50:65]
	v_mfma_f32_32x32x16_bf16 v[34:49], v[124:127], v[202:205], v[34:49]
	v_mfma_f32_32x32x16_bf16 v[18:33], v[128:131], v[202:205], v[18:33]
	s_waitcnt lgkmcnt(0)
	v_mfma_f32_32x32x16_bf16 v[2:17], v[132:135], v[202:205], v[2:17]
	global_load_dwordx4 v[202:205], v[212:213], off offset:-1024
	s_waitcnt vmcnt(15)
	v_mfma_f32_32x32x16_bf16 v[50:65], v[116:119], v[206:209], v[50:65]
	v_mfma_f32_32x32x16_bf16 v[34:49], v[96:99], v[206:209], v[34:49]
	v_mfma_f32_32x32x16_bf16 v[18:33], v[108:111], v[206:209], v[18:33]
	v_mfma_f32_32x32x16_bf16 v[2:17], v[112:115], v[206:209], v[2:17]
	global_load_dwordx4 v[206:209], v[212:213], off offset:0
	v_lshl_add_u64 v[82:83], v[82:83], 0, s[22:23]
	s_add_i32 s25, s25, 16
	s_cmp_gt_u32 s25, 31
	s_cbranch_scc0 .LBB0_972
	s_ashr_i32 s25, s24, 31
	s_mul_i32 s49, s26, 0x24000
	s_lshl_b64 s[28:29], s[24:25], 14
	s_lshl_b64 s[34:35], s[26:27], 19
	s_mul_hi_i32 s31, s26, 0x24000
	s_add_u32 s28, s49, s28
	s_addc_u32 s29, s31, s29
	s_add_u32 s28, s28, 0x800
	s_addc_u32 s29, s29, 0
	s_add_u32 s34, s34, 0x9901000
	s_addc_u32 s35, s35, 0
	v_lshl_add_u64 v[88:89], v[80:81], 0, s[28:29]
	v_lshl_add_u64 v[214:215], v[78:79], 0, s[34:35]
	s_mov_b64 s[28:29], 0x20000
	v_lshl_add_u64 v[216:217], v[214:215], 0, s[28:29]
	v_lshl_add_u64 v[140:141], v[216:217], 0, s[28:29]
	v_lshl_add_u64 v[186:187], v[140:141], 0, s[28:29]
	ds_read_b128 v[84:87], v68 offset:11520
	ds_read_b128 v[96:99], v68 offset:12288
	s_waitcnt vmcnt(15) lgkmcnt(1)
	v_mfma_f32_32x32x16_bf16 v[50:65], v[84:87], v[142:145], v[50:65]
	ds_read_b128 v[84:87], v68 offset:23808
	ds_read_b128 v[108:111], v68 offset:24576
	s_waitcnt lgkmcnt(1)
	v_mfma_f32_32x32x16_bf16 v[34:49], v[84:87], v[142:145], v[34:49]
	ds_read_b128 v[84:87], v68 offset:36096
	ds_read_b128 v[112:115], v68 offset:36864
	s_waitcnt lgkmcnt(1)
	v_mfma_f32_32x32x16_bf16 v[18:33], v[84:87], v[142:145], v[18:33]
	ds_read_b128 v[84:87], v68 offset:48384
	ds_read_b128 v[116:119], v68
	s_waitcnt lgkmcnt(1)
	v_mfma_f32_32x32x16_bf16 v[2:17], v[84:87], v[142:145], v[2:17]
	global_load_dwordx4 v[142:145], v[88:89], off offset:-4096
	ds_read_b128 v[84:87], v68 offset:10752
	ds_read_b128 v[100:103], v68 offset:9984
	s_waitcnt vmcnt(15) lgkmcnt(1)
	v_mfma_f32_32x32x16_bf16 v[50:65], v[84:87], v[146:149], v[50:65]
	ds_read_b128 v[84:87], v68 offset:23040
	ds_read_b128 v[120:123], v68 offset:22272
	s_waitcnt lgkmcnt(1)
	v_mfma_f32_32x32x16_bf16 v[34:49], v[84:87], v[146:149], v[34:49]
	ds_read_b128 v[84:87], v68 offset:35328
	ds_read_b128 v[124:127], v68 offset:34560
	ds_read_b128 v[128:131], v68 offset:46848
	s_waitcnt lgkmcnt(2)
; #define GAS __attribute__((address_space(1)))
; #define LAS __attribute__((address_space(3)))
; __device__ __forceinline__ void ph_s5_out(Frame& F) {
;     ...
;         for (int s0 = 0; s0 < 64; s0 += 16) {
;             bf16x8_t bq[16];
; #pragma unroll
;             for (int e = 0; e < 16; ++e) bq[e] = *(const GAS bf16x8_t*)(ub + 512 * (s0 + e));
; #pragma unroll
;             for (int e = 0; e < 16; ++e) { const int sI = s0 + e; const bf16x8_t b = bq[e];
; #pragma unroll
;             for (int i = 0; i < 4; ++i) { const bf16x8_t a = *(const LAS bf16x8_t*)(tl + (16 * i - sI) * 16 * TP_PITCH); acc[i] = __builtin_amdgcn_mfma_f32_32x32x16_bf16(a, b, acc[i], 0, 0, 0); }
;             }
;         }
;         { const bf16* sb = (const bf16*)(ws + WS_SIN) + (size_t)g * 9 * 16 * 512 + ((size_t)nb * 16 * 64 + lane) * 8;
;           const bf16* wc = (const bf16*)(ws + WS_WC) + (size_t)g * 1024 * 256 + (((size_t)wave * 16) * 64 + lane) * 8;
; #pragma unroll 4
;           for (int kk = 0; kk < 16; ++kk) {
;               const bf16x8_t b = *(const GAS bf16x8_t*)(sb + 512 * kk);
; #pragma unroll
;               for (int i = 0; i < 4; ++i) { const bf16x8_t a = *(const GAS bf16x8_t*)(wc + (size_t)(8 * i) * 16 * 512 + 512 * kk); acc[i] = __builtin_amdgcn_mfma_f32_32x32x16_bf16(a, b, acc[i], 0, 0, 0); }
;           } }
	v_mfma_f32_32x32x16_bf16 v[18:33], v[84:87], v[146:149], v[18:33]
	ds_read_b128 v[84:87], v68 offset:47616
	s_waitcnt lgkmcnt(0)
	v_mfma_f32_32x32x16_bf16 v[2:17], v[84:87], v[146:149], v[2:17]
	global_load_dwordx4 v[146:149], v[214:215], off offset:-4096
	s_waitcnt vmcnt(15)
	v_mfma_f32_32x32x16_bf16 v[50:65], v[100:103], v[150:153], v[50:65]
	v_mfma_f32_32x32x16_bf16 v[34:49], v[120:123], v[150:153], v[34:49]
	ds_read_b128 v[100:103], v68 offset:9216
	ds_read_b128 v[120:123], v68 offset:8448
	v_mfma_f32_32x32x16_bf16 v[18:33], v[124:127], v[150:153], v[18:33]
	v_mfma_f32_32x32x16_bf16 v[2:17], v[128:131], v[150:153], v[2:17]
	global_load_dwordx4 v[150:153], v[216:217], off offset:-4096
	s_waitcnt vmcnt(15) lgkmcnt(1)
	v_mfma_f32_32x32x16_bf16 v[50:65], v[100:103], v[154:157], v[50:65]
	ds_read_b128 v[100:103], v68 offset:21504
	ds_read_b128 v[128:131], v68 offset:20736
	s_waitcnt lgkmcnt(1)
	v_mfma_f32_32x32x16_bf16 v[34:49], v[100:103], v[154:157], v[34:49]
	ds_read_b128 v[100:103], v68 offset:33792
	ds_read_b128 v[132:135], v68 offset:33024
	s_waitcnt lgkmcnt(1)
	v_mfma_f32_32x32x16_bf16 v[18:33], v[100:103], v[154:157], v[18:33]
	ds_read_b128 v[100:103], v68 offset:46080
	ds_read_b128 v[136:139], v68 offset:45312
	s_waitcnt lgkmcnt(1)
	v_mfma_f32_32x32x16_bf16 v[2:17], v[100:103], v[154:157], v[2:17]
	global_load_dwordx4 v[154:157], v[140:141], off offset:-4096
	s_waitcnt vmcnt(15)
	v_mfma_f32_32x32x16_bf16 v[50:65], v[120:123], v[158:161], v[50:65]
	ds_read_b128 v[100:103], v68 offset:7680
	ds_read_b128 v[120:123], v68 offset:6912
	v_mfma_f32_32x32x16_bf16 v[34:49], v[128:131], v[158:161], v[34:49]
	v_mfma_f32_32x32x16_bf16 v[18:33], v[132:135], v[158:161], v[18:33]
	s_waitcnt lgkmcnt(2)
	v_mfma_f32_32x32x16_bf16 v[2:17], v[136:139], v[158:161], v[2:17]
	global_load_dwordx4 v[158:161], v[186:187], off offset:-4096
	s_waitcnt vmcnt(15) lgkmcnt(1)
	v_mfma_f32_32x32x16_bf16 v[50:65], v[100:103], v[162:165], v[50:65]
	ds_read_b128 v[100:103], v68 offset:19968
	ds_read_b128 v[128:131], v68 offset:19200
	s_waitcnt lgkmcnt(1)
	v_mfma_f32_32x32x16_bf16 v[34:49], v[100:103], v[162:165], v[34:49]
	ds_read_b128 v[100:103], v68 offset:32256
	ds_read_b128 v[132:135], v68 offset:31488
	s_waitcnt lgkmcnt(1)
	v_mfma_f32_32x32x16_bf16 v[18:33], v[100:103], v[162:165], v[18:33]
	ds_read_b128 v[100:103], v68 offset:44544
	ds_read_b128 v[136:139], v68 offset:43776
	s_waitcnt lgkmcnt(1)
	v_mfma_f32_32x32x16_bf16 v[2:17], v[100:103], v[162:165], v[2:17]
	global_load_dwordx4 v[162:165], v[88:89], off offset:-3072
	s_waitcnt vmcnt(15)
	v_mfma_f32_32x32x16_bf16 v[50:65], v[120:123], v[166:169], v[50:65]
	ds_read_b128 v[100:103], v68 offset:6144
	ds_read_b128 v[120:123], v68 offset:5376
	v_mfma_f32_32x32x16_bf16 v[34:49], v[128:131], v[166:169], v[34:49]
	v_mfma_f32_32x32x16_bf16 v[18:33], v[132:135], v[166:169], v[18:33]
	s_waitcnt lgkmcnt(2)
	v_mfma_f32_32x32x16_bf16 v[2:17], v[136:139], v[166:169], v[2:17]
	global_load_dwordx4 v[166:169], v[214:215], off offset:-3072
	s_waitcnt vmcnt(15) lgkmcnt(1)
	v_mfma_f32_32x32x16_bf16 v[50:65], v[100:103], v[170:173], v[50:65]
	ds_read_b128 v[100:103], v68 offset:18432
	ds_read_b128 v[124:127], v68 offset:17664
	s_waitcnt lgkmcnt(1)
	v_mfma_f32_32x32x16_bf16 v[34:49], v[100:103], v[170:173], v[34:49]
	ds_read_b128 v[100:103], v68 offset:30720
	ds_read_b128 v[128:131], v68 offset:29952
	s_waitcnt lgkmcnt(1)
	v_mfma_f32_32x32x16_bf16 v[18:33], v[100:103], v[170:173], v[18:33]
	ds_read_b128 v[100:103], v68 offset:43008
	ds_read_b128 v[132:135], v68 offset:42240
	s_waitcnt lgkmcnt(1)
	v_mfma_f32_32x32x16_bf16 v[2:17], v[100:103], v[170:173], v[2:17]
	global_load_dwordx4 v[170:173], v[216:217], off offset:-3072
	ds_read_b128 v[84:87], v68 offset:4608
	ds_read_b128 v[100:103], v68 offset:3840
	s_waitcnt vmcnt(15)
	v_mfma_f32_32x32x16_bf16 v[50:65], v[120:123], v[174:177], v[50:65]
	v_mfma_f32_32x32x16_bf16 v[34:49], v[124:127], v[174:177], v[34:49]
	v_mfma_f32_32x32x16_bf16 v[18:33], v[128:131], v[174:177], v[18:33]
	s_waitcnt lgkmcnt(2)
	v_mfma_f32_32x32x16_bf16 v[2:17], v[132:135], v[174:177], v[2:17]
	global_load_dwordx4 v[174:177], v[140:141], off offset:-3072
	s_waitcnt vmcnt(15) lgkmcnt(1)
	v_mfma_f32_32x32x16_bf16 v[50:65], v[84:87], v[178:181], v[50:65]
	ds_read_b128 v[84:87], v68 offset:16896
	ds_read_b128 v[124:127], v68 offset:16128
	s_waitcnt lgkmcnt(1)
	v_mfma_f32_32x32x16_bf16 v[34:49], v[84:87], v[178:181], v[34:49]
	ds_read_b128 v[84:87], v68 offset:29184
	ds_read_b128 v[128:131], v68 offset:28416
	s_waitcnt lgkmcnt(1)
	v_mfma_f32_32x32x16_bf16 v[18:33], v[84:87], v[178:181], v[18:33]
	ds_read_b128 v[84:87], v68 offset:41472
	ds_read_b128 v[132:135], v68 offset:40704
	s_waitcnt lgkmcnt(1)
	v_mfma_f32_32x32x16_bf16 v[2:17], v[84:87], v[178:181], v[2:17]
	global_load_dwordx4 v[178:181], v[186:187], off offset:-3072
	s_waitcnt vmcnt(15)
	v_mfma_f32_32x32x16_bf16 v[50:65], v[100:103], v[182:185], v[50:65]
	v_mfma_f32_32x32x16_bf16 v[34:49], v[124:127], v[182:185], v[34:49]
	v_mfma_f32_32x32x16_bf16 v[18:33], v[128:131], v[182:185], v[18:33]
	s_waitcnt lgkmcnt(0)
	v_mfma_f32_32x32x16_bf16 v[2:17], v[132:135], v[182:185], v[2:17]
	global_load_dwordx4 v[182:185], v[88:89], off offset:-2048
	ds_read_b128 v[104:107], v68 offset:3072
	ds_read_b128 v[120:123], v68 offset:2304
	s_waitcnt vmcnt(15) lgkmcnt(1)
	v_mfma_f32_32x32x16_bf16 v[50:65], v[104:107], v[190:193], v[50:65]
	ds_read_b128 v[104:107], v68 offset:15360
	ds_read_b128 v[124:127], v68 offset:14592
	s_waitcnt lgkmcnt(1)
	v_mfma_f32_32x32x16_bf16 v[34:49], v[104:107], v[190:193], v[34:49]
	ds_read_b128 v[104:107], v68 offset:27648
	ds_read_b128 v[128:131], v68 offset:26880
	s_waitcnt lgkmcnt(1)
; #define GAS __attribute__((address_space(1)))
; __device__ __forceinline__ void ph_s5_out(Frame& F) {
;     ...
; #pragma unroll 4
;           for (int kk = 0; kk < 16; ++kk) {
;               const bf16x8_t b = *(const GAS bf16x8_t*)(sb + 512 * kk);
; #pragma unroll
;               for (int i = 0; i < 4; ++i) { const bf16x8_t a = *(const GAS bf16x8_t*)(wc + (size_t)(8 * i) * 16 * 512 + 512 * kk); acc[i] = __builtin_amdgcn_mfma_f32_32x32x16_bf16(a, b, acc[i], 0, 0, 0); }
;           } }
	v_mfma_f32_32x32x16_bf16 v[18:33], v[104:107], v[190:193], v[18:33]
	ds_read_b128 v[104:107], v68 offset:39936
	ds_read_b128 v[132:135], v68 offset:39168
	s_waitcnt lgkmcnt(1)
	v_mfma_f32_32x32x16_bf16 v[2:17], v[104:107], v[190:193], v[2:17]
	global_load_dwordx4 v[190:193], v[214:215], off offset:-2048
	s_waitcnt vmcnt(15)
	v_mfma_f32_32x32x16_bf16 v[50:65], v[120:123], v[194:197], v[50:65]
	v_mfma_f32_32x32x16_bf16 v[34:49], v[124:127], v[194:197], v[34:49]
	v_mfma_f32_32x32x16_bf16 v[18:33], v[128:131], v[194:197], v[18:33]
	s_waitcnt lgkmcnt(0)
	v_mfma_f32_32x32x16_bf16 v[2:17], v[132:135], v[194:197], v[2:17]
	global_load_dwordx4 v[194:197], v[216:217], off offset:-2048
	ds_read_b128 v[100:103], v68 offset:1536
	ds_read_b128 v[120:123], v68 offset:768
	s_waitcnt vmcnt(15) lgkmcnt(1)
	v_mfma_f32_32x32x16_bf16 v[50:65], v[100:103], v[198:201], v[50:65]
	ds_read_b128 v[100:103], v68 offset:13824
	ds_read_b128 v[124:127], v68 offset:13056
	s_waitcnt lgkmcnt(1)
	v_mfma_f32_32x32x16_bf16 v[34:49], v[100:103], v[198:201], v[34:49]
	ds_read_b128 v[100:103], v68 offset:26112
	ds_read_b128 v[128:131], v68 offset:25344
	s_waitcnt lgkmcnt(1)
	v_mfma_f32_32x32x16_bf16 v[18:33], v[100:103], v[198:201], v[18:33]
	ds_read_b128 v[100:103], v68 offset:38400
	ds_read_b128 v[132:135], v68 offset:37632
	v_add_u32_e32 v68, 0xffffd000, v68
	s_waitcnt lgkmcnt(1)
	v_mfma_f32_32x32x16_bf16 v[2:17], v[100:103], v[198:201], v[2:17]
	global_load_dwordx4 v[198:201], v[140:141], off offset:-2048
	s_waitcnt vmcnt(15)
	v_mfma_f32_32x32x16_bf16 v[50:65], v[120:123], v[202:205], v[50:65]
	v_mfma_f32_32x32x16_bf16 v[34:49], v[124:127], v[202:205], v[34:49]
	v_mfma_f32_32x32x16_bf16 v[18:33], v[128:131], v[202:205], v[18:33]
	s_waitcnt lgkmcnt(0)
	v_mfma_f32_32x32x16_bf16 v[2:17], v[132:135], v[202:205], v[2:17]
	global_load_dwordx4 v[202:205], v[186:187], off offset:-2048
	s_waitcnt vmcnt(15)
	v_mfma_f32_32x32x16_bf16 v[50:65], v[116:119], v[206:209], v[50:65]
	v_mfma_f32_32x32x16_bf16 v[34:49], v[96:99], v[206:209], v[34:49]
	v_mfma_f32_32x32x16_bf16 v[18:33], v[108:111], v[206:209], v[18:33]
	v_mfma_f32_32x32x16_bf16 v[2:17], v[112:115], v[206:209], v[2:17]
	global_load_dwordx4 v[206:209], v[88:89], off offset:-1024
	global_load_dwordx4 v[96:99], v[214:215], off offset:-1024
	global_load_dwordx4 v[100:103], v[216:217], off offset:-1024
	global_load_dwordx4 v[104:107], v[140:141], off offset:-1024
	global_load_dwordx4 v[108:111], v[186:187], off offset:-1024
	global_load_dwordx4 v[112:115], v[88:89], off
	global_load_dwordx4 v[116:119], v[214:215], off
	global_load_dwordx4 v[120:123], v[216:217], off
	global_load_dwordx4 v[124:127], v[140:141], off
	global_load_dwordx4 v[128:131], v[186:187], off
	global_load_dwordx4 v[132:135], v[88:89], off offset:1024
	global_load_dwordx4 v[136:139], v[214:215], off offset:1024
	s_waitcnt vmcnt(25)
	v_mfma_f32_32x32x16_bf16 v[50:65], v[146:149], v[142:145], v[50:65]
	global_load_dwordx4 v[146:149], v[216:217], off offset:1024
	s_waitcnt vmcnt(25)
	v_mfma_f32_32x32x16_bf16 v[34:49], v[150:153], v[142:145], v[34:49]
	global_load_dwordx4 v[150:153], v[140:141], off offset:1024
	s_waitcnt vmcnt(25)
	v_mfma_f32_32x32x16_bf16 v[18:33], v[154:157], v[142:145], v[18:33]
	global_load_dwordx4 v[154:157], v[186:187], off offset:1024
	s_waitcnt vmcnt(25)
	v_mfma_f32_32x32x16_bf16 v[2:17], v[158:161], v[142:145], v[2:17]
	global_load_dwordx4 v[158:161], v[88:89], off offset:2048
	global_load_dwordx4 v[142:145], v[214:215], off offset:2048
	s_waitcnt vmcnt(25)
	v_mfma_f32_32x32x16_bf16 v[50:65], v[166:169], v[162:165], v[50:65]
	global_load_dwordx4 v[166:169], v[216:217], off offset:2048
	s_waitcnt vmcnt(25)
	v_mfma_f32_32x32x16_bf16 v[34:49], v[170:173], v[162:165], v[34:49]
	global_load_dwordx4 v[170:173], v[140:141], off offset:2048
	s_waitcnt vmcnt(25)
	v_mfma_f32_32x32x16_bf16 v[18:33], v[174:177], v[162:165], v[18:33]
	global_load_dwordx4 v[174:177], v[186:187], off offset:2048
	s_waitcnt vmcnt(25)
	v_mfma_f32_32x32x16_bf16 v[2:17], v[178:181], v[162:165], v[2:17]
	global_load_dwordx4 v[178:181], v[88:89], off offset:3072
	global_load_dwordx4 v[162:165], v[214:215], off offset:3072
	s_waitcnt vmcnt(25)
	v_mfma_f32_32x32x16_bf16 v[50:65], v[190:193], v[182:185], v[50:65]
	global_load_dwordx4 v[190:193], v[216:217], off offset:3072
	s_waitcnt vmcnt(25)
	v_mfma_f32_32x32x16_bf16 v[34:49], v[194:197], v[182:185], v[34:49]
	global_load_dwordx4 v[194:197], v[140:141], off offset:3072
	s_waitcnt vmcnt(25)
	v_mfma_f32_32x32x16_bf16 v[18:33], v[198:201], v[182:185], v[18:33]
	global_load_dwordx4 v[198:201], v[186:187], off offset:3072
	s_waitcnt vmcnt(25)
	v_mfma_f32_32x32x16_bf16 v[2:17], v[202:205], v[182:185], v[2:17]
	v_lshl_add_u64 v[88:89], v[88:89], 0, s[20:21]
	v_lshl_add_u64 v[214:215], v[214:215], 0, s[20:21]
	v_lshl_add_u64 v[216:217], v[216:217], 0, s[20:21]
	v_lshl_add_u64 v[140:141], v[140:141], 0, s[20:21]
	v_lshl_add_u64 v[186:187], v[186:187], 0, s[20:21]
	global_load_dwordx4 v[202:205], v[88:89], off offset:-4096
	global_load_dwordx4 v[182:185], v[214:215], off offset:-4096
	s_waitcnt vmcnt(25)
	v_mfma_f32_32x32x16_bf16 v[50:65], v[96:99], v[206:209], v[50:65]
	global_load_dwordx4 v[96:99], v[216:217], off offset:-4096
	s_waitcnt vmcnt(25)
	v_mfma_f32_32x32x16_bf16 v[34:49], v[100:103], v[206:209], v[34:49]
	global_load_dwordx4 v[100:103], v[140:141], off offset:-4096
	s_waitcnt vmcnt(25)
	v_mfma_f32_32x32x16_bf16 v[18:33], v[104:107], v[206:209], v[18:33]
	global_load_dwordx4 v[104:107], v[186:187], off offset:-4096
	s_waitcnt vmcnt(25)
; #define GAS __attribute__((address_space(1)))
; __device__ __forceinline__ void ph_s5_out(Frame& F) {
;     ...
; #pragma unroll 4
;           for (int kk = 0; kk < 16; ++kk) {
;               const bf16x8_t b = *(const GAS bf16x8_t*)(sb + 512 * kk);
; #pragma unroll
;               for (int i = 0; i < 4; ++i) { const bf16x8_t a = *(const GAS bf16x8_t*)(wc + (size_t)(8 * i) * 16 * 512 + 512 * kk); acc[i] = __builtin_amdgcn_mfma_f32_32x32x16_bf16(a, b, acc[i], 0, 0, 0); }
;           } }
;         if (valid) {
	v_mfma_f32_32x32x16_bf16 v[2:17], v[108:111], v[206:209], v[2:17]
	global_load_dwordx4 v[108:111], v[88:89], off offset:-3072
	global_load_dwordx4 v[206:209], v[214:215], off offset:-3072
	s_waitcnt vmcnt(25)
	v_mfma_f32_32x32x16_bf16 v[50:65], v[116:119], v[112:115], v[50:65]
	global_load_dwordx4 v[116:119], v[216:217], off offset:-3072
	s_waitcnt vmcnt(25)
	v_mfma_f32_32x32x16_bf16 v[34:49], v[120:123], v[112:115], v[34:49]
	global_load_dwordx4 v[120:123], v[140:141], off offset:-3072
	s_waitcnt vmcnt(25)
	v_mfma_f32_32x32x16_bf16 v[18:33], v[124:127], v[112:115], v[18:33]
	global_load_dwordx4 v[124:127], v[186:187], off offset:-3072
	s_waitcnt vmcnt(25)
	v_mfma_f32_32x32x16_bf16 v[2:17], v[128:131], v[112:115], v[2:17]
	global_load_dwordx4 v[128:131], v[88:89], off offset:-2048
	global_load_dwordx4 v[112:115], v[214:215], off offset:-2048
	s_waitcnt vmcnt(25)
	v_mfma_f32_32x32x16_bf16 v[50:65], v[136:139], v[132:135], v[50:65]
	global_load_dwordx4 v[136:139], v[216:217], off offset:-2048
	s_waitcnt vmcnt(25)
	v_mfma_f32_32x32x16_bf16 v[34:49], v[146:149], v[132:135], v[34:49]
	global_load_dwordx4 v[146:149], v[140:141], off offset:-2048
	s_waitcnt vmcnt(25)
	v_mfma_f32_32x32x16_bf16 v[18:33], v[150:153], v[132:135], v[18:33]
	global_load_dwordx4 v[150:153], v[186:187], off offset:-2048
	s_waitcnt vmcnt(25)
	v_mfma_f32_32x32x16_bf16 v[2:17], v[154:157], v[132:135], v[2:17]
	global_load_dwordx4 v[154:157], v[88:89], off offset:-1024
	global_load_dwordx4 v[132:135], v[214:215], off offset:-1024
	s_waitcnt vmcnt(25)
	v_mfma_f32_32x32x16_bf16 v[50:65], v[142:145], v[158:161], v[50:65]
	global_load_dwordx4 v[142:145], v[216:217], off offset:-1024
	s_waitcnt vmcnt(25)
	v_mfma_f32_32x32x16_bf16 v[34:49], v[166:169], v[158:161], v[34:49]
	global_load_dwordx4 v[166:169], v[140:141], off offset:-1024
	s_waitcnt vmcnt(25)
	v_mfma_f32_32x32x16_bf16 v[18:33], v[170:173], v[158:161], v[18:33]
	global_load_dwordx4 v[170:173], v[186:187], off offset:-1024
	s_waitcnt vmcnt(25)
	v_mfma_f32_32x32x16_bf16 v[2:17], v[174:177], v[158:161], v[2:17]
	global_load_dwordx4 v[174:177], v[88:89], off
	global_load_dwordx4 v[158:161], v[214:215], off
	s_waitcnt vmcnt(25)
	v_mfma_f32_32x32x16_bf16 v[50:65], v[162:165], v[178:181], v[50:65]
	global_load_dwordx4 v[162:165], v[216:217], off
	s_waitcnt vmcnt(25)
	v_mfma_f32_32x32x16_bf16 v[34:49], v[190:193], v[178:181], v[34:49]
	global_load_dwordx4 v[190:193], v[140:141], off
	s_waitcnt vmcnt(25)
	v_mfma_f32_32x32x16_bf16 v[18:33], v[194:197], v[178:181], v[18:33]
	global_load_dwordx4 v[194:197], v[186:187], off
	s_waitcnt vmcnt(25)
	v_mfma_f32_32x32x16_bf16 v[2:17], v[198:201], v[178:181], v[2:17]
	global_load_dwordx4 v[198:201], v[88:89], off offset:1024
	global_load_dwordx4 v[178:181], v[214:215], off offset:1024
	s_waitcnt vmcnt(25)
	v_mfma_f32_32x32x16_bf16 v[50:65], v[182:185], v[202:205], v[50:65]
	global_load_dwordx4 v[182:185], v[216:217], off offset:1024
	s_waitcnt vmcnt(25)
	v_mfma_f32_32x32x16_bf16 v[34:49], v[96:99], v[202:205], v[34:49]
	global_load_dwordx4 v[96:99], v[140:141], off offset:1024
	s_waitcnt vmcnt(25)
	v_mfma_f32_32x32x16_bf16 v[18:33], v[100:103], v[202:205], v[18:33]
	global_load_dwordx4 v[100:103], v[186:187], off offset:1024
	s_waitcnt vmcnt(25)
	v_mfma_f32_32x32x16_bf16 v[2:17], v[104:107], v[202:205], v[2:17]
	global_load_dwordx4 v[104:107], v[88:89], off offset:2048
	global_load_dwordx4 v[202:205], v[214:215], off offset:2048
	s_waitcnt vmcnt(25)
	v_mfma_f32_32x32x16_bf16 v[50:65], v[206:209], v[108:111], v[50:65]
	global_load_dwordx4 v[206:209], v[216:217], off offset:2048
	s_waitcnt vmcnt(25)
	v_mfma_f32_32x32x16_bf16 v[34:49], v[116:119], v[108:111], v[34:49]
	global_load_dwordx4 v[116:119], v[140:141], off offset:2048
	s_waitcnt vmcnt(25)
	v_mfma_f32_32x32x16_bf16 v[18:33], v[120:123], v[108:111], v[18:33]
	global_load_dwordx4 v[120:123], v[186:187], off offset:2048
	s_waitcnt vmcnt(25)
	v_mfma_f32_32x32x16_bf16 v[2:17], v[124:127], v[108:111], v[2:17]
	global_load_dwordx4 v[124:127], v[88:89], off offset:3072
	global_load_dwordx4 v[108:111], v[214:215], off offset:3072
	s_waitcnt vmcnt(25)
	v_mfma_f32_32x32x16_bf16 v[50:65], v[112:115], v[128:131], v[50:65]
	global_load_dwordx4 v[112:115], v[216:217], off offset:3072
	s_waitcnt vmcnt(25)
	v_mfma_f32_32x32x16_bf16 v[34:49], v[136:139], v[128:131], v[34:49]
	global_load_dwordx4 v[136:139], v[140:141], off offset:3072
	s_waitcnt vmcnt(25)
	v_mfma_f32_32x32x16_bf16 v[18:33], v[146:149], v[128:131], v[18:33]
	global_load_dwordx4 v[146:149], v[186:187], off offset:3072
	s_waitcnt vmcnt(25)
	v_mfma_f32_32x32x16_bf16 v[2:17], v[150:153], v[128:131], v[2:17]
	s_waitcnt vmcnt(23)
	v_mfma_f32_32x32x16_bf16 v[50:65], v[132:135], v[154:157], v[50:65]
	s_waitcnt vmcnt(22)
	v_mfma_f32_32x32x16_bf16 v[34:49], v[142:145], v[154:157], v[34:49]
	s_waitcnt vmcnt(21)
	v_mfma_f32_32x32x16_bf16 v[18:33], v[166:169], v[154:157], v[18:33]
	s_waitcnt vmcnt(20)
	v_mfma_f32_32x32x16_bf16 v[2:17], v[170:173], v[154:157], v[2:17]
	s_waitcnt vmcnt(18)
	v_mfma_f32_32x32x16_bf16 v[50:65], v[158:161], v[174:177], v[50:65]
	s_waitcnt vmcnt(17)
	v_mfma_f32_32x32x16_bf16 v[34:49], v[162:165], v[174:177], v[34:49]
	s_waitcnt vmcnt(16)
	v_mfma_f32_32x32x16_bf16 v[18:33], v[190:193], v[174:177], v[18:33]
	s_waitcnt vmcnt(15)
	v_mfma_f32_32x32x16_bf16 v[2:17], v[194:197], v[174:177], v[2:17]
	s_waitcnt vmcnt(13)
	v_mfma_f32_32x32x16_bf16 v[50:65], v[178:181], v[198:201], v[50:65]
	s_waitcnt vmcnt(12)
	v_mfma_f32_32x32x16_bf16 v[34:49], v[182:185], v[198:201], v[34:49]
	s_waitcnt vmcnt(11)
	v_mfma_f32_32x32x16_bf16 v[18:33], v[96:99], v[198:201], v[18:33]
	s_waitcnt vmcnt(10)
	v_mfma_f32_32x32x16_bf16 v[2:17], v[100:103], v[198:201], v[2:17]
	s_waitcnt vmcnt(8)
	v_mfma_f32_32x32x16_bf16 v[50:65], v[202:205], v[104:107], v[50:65]
	s_waitcnt vmcnt(7)
	v_mfma_f32_32x32x16_bf16 v[34:49], v[206:209], v[104:107], v[34:49]
	s_waitcnt vmcnt(6)
	v_mfma_f32_32x32x16_bf16 v[18:33], v[116:119], v[104:107], v[18:33]
	s_waitcnt vmcnt(5)
	v_mfma_f32_32x32x16_bf16 v[2:17], v[120:123], v[104:107], v[2:17]
	s_waitcnt vmcnt(3)
	v_mfma_f32_32x32x16_bf16 v[50:65], v[108:111], v[124:127], v[50:65]
	s_waitcnt vmcnt(2)
	v_mfma_f32_32x32x16_bf16 v[34:49], v[112:115], v[124:127], v[34:49]
	s_waitcnt vmcnt(1)
	v_mfma_f32_32x32x16_bf16 v[18:33], v[136:139], v[124:127], v[18:33]
	s_waitcnt vmcnt(0)
	v_mfma_f32_32x32x16_bf16 v[2:17], v[146:149], v[124:127], v[2:17]
	v_lshl_or_b32 v82, s24, 5, v1
	v_cmp_gt_i32_e32 vcc, s45, v82
	s_and_saveexec_b64 s[24:25], vcc
	s_cbranch_execz .LBB0_963
; #define GAS __attribute__((address_space(1)))
; __device__ __forceinline__ unsigned pk2(float lo, float hi) { const f32x2cv v = {lo, hi}; return __builtin_bit_cast(unsigned, __builtin_convertvector(v, bf16x2cv)); }
; __device__ __forceinline__ float gelu_tanh(float x) { const float u = 0.7978845608028654f * (x + 0.044715f * x * x * x); return x * __builtin_amdgcn_rcpf(1.0f + __builtin_amdgcn_exp2f(-2.8853900817779268f * u)); }
; __device__ __forceinline__ void ph_s5_out(Frame& F) {
;     ...
;         if (valid) {
;             const float* dsk = inp(F, 24) + 16 * g;
; #pragma unroll
;             for (int i = 0; i < 4; ++i)
; #pragma unroll
;                 for (int k = 0; k < 4; ++k) { const int tloc = 2 * (wave + 8 * i) + (k >> 1), p0 = 8 * (k & 1) + 4 * hh; const size_t m = (size_t)chunk * 64 + tloc;
;                     const v2u uw = *(const GAS v2u*)((chunk < 256 ? (const bf16*)(ws + WS_UG) : (const bf16*)(ws + WS_UGC)) + ug_index(g, (int)m, p0));
;                     const float y0 = gelu_tanh(acc[i][4 * k] + dsk[p0] * bflo(uw.x)), y1 = gelu_tanh(acc[i][4 * k + 1] + dsk[p0 + 1] * bfhi(uw.x));
;                     const float y2 = gelu_tanh(acc[i][4 * k + 2] + dsk[p0 + 2] * bflo(uw.y)), y3 = gelu_tanh(acc[i][4 * k + 3] + dsk[p0 + 3] * bfhi(uw.y));
;                     v2u zw; zw.x = pk2(y0, y1); zw.y = pk2(y2, y3);
;                     *(GAS v2u*)((bf16*)(ws + WS_Z) + m * 512 + 16 * g + p0) = zw; }
	v_mov_b32_e32 v68, s46
	ds_read_b64 v[84:85], v68
	v_ashrrev_i32_e32 v83, 31, v82
	v_lshlrev_b64 v[88:89], 6, v[82:83]
	v_cmp_gt_i32_e32 vcc, s47, v82
	v_lshl_add_u64 v[102:103], v[88:89], 0, s[4:5]
	v_ashrrev_i32_e32 v83, 11, v102
	v_cndmask_b32_e32 v68, v94, v95, vcc
	v_lshl_add_u64 v[86:87], v[70:71], 0, v[68:69]
	v_ashrrev_i32_e32 v68, 6, v102
	v_add_u32_e32 v83, s30, v83
	v_mov_b32_e32 v96, s26
	v_cmp_gt_i32_e32 vcc, s47, v68
	s_lshl_b32 s28, s26, 4
	s_waitcnt lgkmcnt(0)
	v_readfirstlane_b32 s27, v84
	v_and_b32_e32 v97, 31, v68
	v_cndmask_b32_e32 v84, v96, v83, vcc
	s_ashr_i32 s29, s28, 31
	v_readfirstlane_b32 s31, v85
	v_or_b32_e32 v82, v97, v67
	v_ashrrev_i32_e32 v85, 31, v84
	v_lshlrev_b32_e32 v68, 6, v102
	s_lshl_b64 s[34:35], s[28:29], 2
	v_and_b32_e32 v68, 0xf80, v68
	v_ashrrev_i32_e32 v83, 31, v82
	v_lshlrev_b64 v[84:85], 16, v[84:85]
	v_lshl_add_u64 v[82:83], v[68:69], 0, v[82:83]
	v_lshl_add_u64 v[104:105], v[86:87], 0, v[84:85]
	s_add_u32 s26, s27, s34
	v_lshl_add_u64 v[82:83], v[82:83], 4, v[104:105]
	s_addc_u32 s27, s31, s35
	v_lshl_add_u64 v[98:99], v[188:189], 2, s[26:27]
	global_load_dwordx4 v[174:177], v[98:99], off
	global_load_dwordx4 v[178:181], v[98:99], off offset:32
	global_load_dwordx2 v[142:143], v[82:83], off
	global_load_dwordx2 v[144:145], v[82:83], off offset:512
	global_load_dwordx2 v[146:147], v[82:83], off offset:1024
	global_load_dwordx2 v[148:149], v[82:83], off offset:1536
	v_lshl_add_u64 v[82:83], v[82:83], 0, s[22:23]
	global_load_dwordx2 v[150:151], v[82:83], off
	global_load_dwordx2 v[152:153], v[82:83], off offset:512
	global_load_dwordx2 v[154:155], v[82:83], off offset:1024
	global_load_dwordx2 v[156:157], v[82:83], off offset:1536
	v_lshl_add_u64 v[82:83], v[82:83], 0, s[22:23]
	global_load_dwordx2 v[158:159], v[82:83], off
	global_load_dwordx2 v[160:161], v[82:83], off offset:512
	global_load_dwordx2 v[162:163], v[82:83], off offset:1024
	global_load_dwordx2 v[164:165], v[82:83], off offset:1536
	v_lshl_add_u64 v[82:83], v[82:83], 0, s[22:23]
	global_load_dwordx2 v[166:167], v[82:83], off
	global_load_dwordx2 v[168:169], v[82:83], off offset:512
	global_load_dwordx2 v[170:171], v[82:83], off offset:1024
	global_load_dwordx2 v[172:173], v[82:83], off offset:1536
	s_lshl_b64 s[26:27], s[28:29], 1
	s_add_u32 s26, s38, s26
	v_lshlrev_b64 v[102:103], 10, v[102:103]
	s_addc_u32 s27, s39, s27
	v_lshlrev_b64 v[84:85], 1, v[188:189]
	v_lshl_add_u64 v[102:103], s[26:27], 0, v[102:103]
	v_lshl_add_u64 v[102:103], v[102:103], 0, v[84:85]
	v_lshl_add_u64 v[102:103], v[188:189], 1, v[102:103]
	s_waitcnt vmcnt(15)
	v_lshlrev_b32_e32 v182, 16, v142
	v_and_b32_e32 v183, 0xffff0000, v142
	v_lshlrev_b32_e32 v184, 16, v143
	v_and_b32_e32 v185, 0xffff0000, v143
	v_pk_fma_f32 v[194:195], v[174:175], v[182:183], v[50:51]
	v_pk_fma_f32 v[200:201], v[176:177], v[184:185], v[52:53]
	v_mul_f32_e32 v190, 0x3d372713, v194
	v_mul_f32_e32 v191, 0x3d372713, v195
	v_mul_f32_e32 v192, 0x3d372713, v200
	v_mul_f32_e32 v193, 0x3d372713, v201
	v_mul_f32_e32 v190, v194, v190
	v_mul_f32_e32 v191, v195, v191
	v_mul_f32_e32 v192, v200, v192
	v_mul_f32_e32 v193, v201, v193
	v_fma_f32 v190, v194, v190, v194
	v_fma_f32 v191, v195, v191, v195
	v_fma_f32 v192, v200, v192, v200
	v_fma_f32 v193, v201, v193, v201
	v_mul_f32_e32 v190, 0x3f4c422a, v190
	v_mul_f32_e32 v191, 0x3f4c422a, v191
	v_mul_f32_e32 v192, 0x3f4c422a, v192
	v_mul_f32_e32 v193, 0x3f4c422a, v193
	v_mul_f32_e32 v190, 0xc038aa3b, v190
	v_mul_f32_e32 v191, 0xc038aa3b, v191
	v_mul_f32_e32 v192, 0xc038aa3b, v192
	v_mul_f32_e32 v193, 0xc038aa3b, v193
	v_exp_f32_e32 v190, v190
	v_exp_f32_e32 v191, v191
	v_exp_f32_e32 v192, v192
	v_exp_f32_e32 v193, v193
	v_add_f32_e32 v190, 1.0, v190
	v_add_f32_e32 v191, 1.0, v191
	v_add_f32_e32 v192, 1.0, v192
	v_add_f32_e32 v193, 1.0, v193
	v_rcp_f32_e32 v190, v190
	v_rcp_f32_e32 v191, v191
	v_rcp_f32_e32 v192, v192
	v_rcp_f32_e32 v193, v193
	v_pk_mul_f32 v[194:195], v[194:195], v[190:191]
	v_pk_mul_f32 v[200:201], v[200:201], v[192:193]
	v_cvt_pk_bf16_f32 v196, v194, v195
	v_cvt_pk_bf16_f32 v197, v200, v201
	s_waitcnt vmcnt(14)
	v_lshlrev_b32_e32 v182, 16, v144
	v_and_b32_e32 v183, 0xffff0000, v144
	v_lshlrev_b32_e32 v184, 16, v145
	v_and_b32_e32 v185, 0xffff0000, v145
	v_pk_fma_f32 v[194:195], v[178:179], v[182:183], v[54:55]
	v_pk_fma_f32 v[200:201], v[180:181], v[184:185], v[56:57]
	v_mul_f32_e32 v190, 0x3d372713, v194
	v_mul_f32_e32 v191, 0x3d372713, v195
	v_mul_f32_e32 v192, 0x3d372713, v200
	v_mul_f32_e32 v193, 0x3d372713, v201
	v_mul_f32_e32 v190, v194, v190
	v_mul_f32_e32 v191, v195, v191
	v_mul_f32_e32 v192, v200, v192
	v_mul_f32_e32 v193, v201, v193
	v_fma_f32 v190, v194, v190, v194
	v_fma_f32 v191, v195, v191, v195
	v_fma_f32 v192, v200, v192, v200
	v_fma_f32 v193, v201, v193, v201
	v_mul_f32_e32 v190, 0x3f4c422a, v190
	v_mul_f32_e32 v191, 0x3f4c422a, v191
	v_mul_f32_e32 v192, 0x3f4c422a, v192
	v_mul_f32_e32 v193, 0x3f4c422a, v193
	v_mul_f32_e32 v190, 0xc038aa3b, v190
	v_mul_f32_e32 v191, 0xc038aa3b, v191
	v_mul_f32_e32 v192, 0xc038aa3b, v192
	v_mul_f32_e32 v193, 0xc038aa3b, v193
	v_exp_f32_e32 v190, v190
	v_exp_f32_e32 v191, v191
	v_exp_f32_e32 v192, v192
	v_exp_f32_e32 v193, v193
	v_add_f32_e32 v190, 1.0, v190
	v_add_f32_e32 v191, 1.0, v191
	v_add_f32_e32 v192, 1.0, v192
	v_add_f32_e32 v193, 1.0, v193
	v_rcp_f32_e32 v190, v190
	v_rcp_f32_e32 v191, v191
	v_rcp_f32_e32 v192, v192
	v_rcp_f32_e32 v193, v193
	v_pk_mul_f32 v[194:195], v[194:195], v[190:191]
	v_pk_mul_f32 v[200:201], v[200:201], v[192:193]
	v_cvt_pk_bf16_f32 v198, v194, v195
	v_cvt_pk_bf16_f32 v199, v200, v201
	s_nop 1
	v_permlane32_swap_b32_e32 v196, v198
	v_permlane32_swap_b32_e32 v197, v199
	global_store_dwordx4 v[102:103], v[196:199], off
	s_waitcnt vmcnt(14)
; #define GAS __attribute__((address_space(1)))
; __device__ __forceinline__ unsigned pk2(float lo, float hi) { const f32x2cv v = {lo, hi}; return __builtin_bit_cast(unsigned, __builtin_convertvector(v, bf16x2cv)); }
; __device__ __forceinline__ float gelu_tanh(float x) { const float u = 0.7978845608028654f * (x + 0.044715f * x * x * x); return x * __builtin_amdgcn_rcpf(1.0f + __builtin_amdgcn_exp2f(-2.8853900817779268f * u)); }
; __device__ __forceinline__ void ph_s5_out(Frame& F) {
;     ...
;                 for (int k = 0; k < 4; ++k) { const int tloc = 2 * (wave + 8 * i) + (k >> 1), p0 = 8 * (k & 1) + 4 * hh; const size_t m = (size_t)chunk * 64 + tloc;
;                     const v2u uw = *(const GAS v2u*)((chunk < 256 ? (const bf16*)(ws + WS_UG) : (const bf16*)(ws + WS_UGC)) + ug_index(g, (int)m, p0));
;                     const float y0 = gelu_tanh(acc[i][4 * k] + dsk[p0] * bflo(uw.x)), y1 = gelu_tanh(acc[i][4 * k + 1] + dsk[p0 + 1] * bfhi(uw.x));
;                     const float y2 = gelu_tanh(acc[i][4 * k + 2] + dsk[p0 + 2] * bflo(uw.y)), y3 = gelu_tanh(acc[i][4 * k + 3] + dsk[p0 + 3] * bfhi(uw.y));
;                     v2u zw; zw.x = pk2(y0, y1); zw.y = pk2(y2, y3);
;                     *(GAS v2u*)((bf16*)(ws + WS_Z) + m * 512 + 16 * g + p0) = zw; }
	v_lshlrev_b32_e32 v182, 16, v146
	v_and_b32_e32 v183, 0xffff0000, v146
	v_lshlrev_b32_e32 v184, 16, v147
	v_and_b32_e32 v185, 0xffff0000, v147
	v_pk_fma_f32 v[194:195], v[174:175], v[182:183], v[58:59]
	v_pk_fma_f32 v[200:201], v[176:177], v[184:185], v[60:61]
	v_mul_f32_e32 v190, 0x3d372713, v194
	v_mul_f32_e32 v191, 0x3d372713, v195
	v_mul_f32_e32 v192, 0x3d372713, v200
	v_mul_f32_e32 v193, 0x3d372713, v201
	v_mul_f32_e32 v190, v194, v190
	v_mul_f32_e32 v191, v195, v191
	v_mul_f32_e32 v192, v200, v192
	v_mul_f32_e32 v193, v201, v193
	v_fma_f32 v190, v194, v190, v194
	v_fma_f32 v191, v195, v191, v195
	v_fma_f32 v192, v200, v192, v200
	v_fma_f32 v193, v201, v193, v201
	v_mul_f32_e32 v190, 0x3f4c422a, v190
	v_mul_f32_e32 v191, 0x3f4c422a, v191
	v_mul_f32_e32 v192, 0x3f4c422a, v192
	v_mul_f32_e32 v193, 0x3f4c422a, v193
	v_mul_f32_e32 v190, 0xc038aa3b, v190
	v_mul_f32_e32 v191, 0xc038aa3b, v191
	v_mul_f32_e32 v192, 0xc038aa3b, v192
	v_mul_f32_e32 v193, 0xc038aa3b, v193
	v_exp_f32_e32 v190, v190
	v_exp_f32_e32 v191, v191
	v_exp_f32_e32 v192, v192
	v_exp_f32_e32 v193, v193
	v_add_f32_e32 v190, 1.0, v190
	v_add_f32_e32 v191, 1.0, v191
	v_add_f32_e32 v192, 1.0, v192
	v_add_f32_e32 v193, 1.0, v193
	v_rcp_f32_e32 v190, v190
	v_rcp_f32_e32 v191, v191
	v_rcp_f32_e32 v192, v192
	v_rcp_f32_e32 v193, v193
	v_pk_mul_f32 v[194:195], v[194:195], v[190:191]
	v_pk_mul_f32 v[200:201], v[200:201], v[192:193]
	v_cvt_pk_bf16_f32 v196, v194, v195
	v_cvt_pk_bf16_f32 v197, v200, v201
	s_waitcnt vmcnt(13)
	v_lshlrev_b32_e32 v182, 16, v148
	v_and_b32_e32 v183, 0xffff0000, v148
	v_lshlrev_b32_e32 v184, 16, v149
	v_and_b32_e32 v185, 0xffff0000, v149
	v_pk_fma_f32 v[194:195], v[178:179], v[182:183], v[62:63]
	v_pk_fma_f32 v[200:201], v[180:181], v[184:185], v[64:65]
	v_mul_f32_e32 v190, 0x3d372713, v194
	v_mul_f32_e32 v191, 0x3d372713, v195
	v_mul_f32_e32 v192, 0x3d372713, v200
	v_mul_f32_e32 v193, 0x3d372713, v201
	v_mul_f32_e32 v190, v194, v190
	v_mul_f32_e32 v191, v195, v191
	v_mul_f32_e32 v192, v200, v192
	v_mul_f32_e32 v193, v201, v193
	v_fma_f32 v190, v194, v190, v194
	v_fma_f32 v191, v195, v191, v195
	v_fma_f32 v192, v200, v192, v200
	v_fma_f32 v193, v201, v193, v201
	v_mul_f32_e32 v190, 0x3f4c422a, v190
	v_mul_f32_e32 v191, 0x3f4c422a, v191
	v_mul_f32_e32 v192, 0x3f4c422a, v192
	v_mul_f32_e32 v193, 0x3f4c422a, v193
	v_mul_f32_e32 v190, 0xc038aa3b, v190
	v_mul_f32_e32 v191, 0xc038aa3b, v191
	v_mul_f32_e32 v192, 0xc038aa3b, v192
	v_mul_f32_e32 v193, 0xc038aa3b, v193
	v_exp_f32_e32 v190, v190
	v_exp_f32_e32 v191, v191
	v_exp_f32_e32 v192, v192
	v_exp_f32_e32 v193, v193
	v_add_f32_e32 v190, 1.0, v190
	v_add_f32_e32 v191, 1.0, v191
	v_add_f32_e32 v192, 1.0, v192
	v_add_f32_e32 v193, 1.0, v193
	v_rcp_f32_e32 v190, v190
	v_rcp_f32_e32 v191, v191
	v_rcp_f32_e32 v192, v192
	v_rcp_f32_e32 v193, v193
	v_pk_mul_f32 v[194:195], v[194:195], v[190:191]
	v_pk_mul_f32 v[200:201], v[200:201], v[192:193]
	v_cvt_pk_bf16_f32 v198, v194, v195
	v_cvt_pk_bf16_f32 v199, v200, v201
	s_nop 1
	v_permlane32_swap_b32_e32 v196, v198
	v_permlane32_swap_b32_e32 v197, v199
	global_store_dwordx4 v[102:103], v[196:199], off offset:1024
	v_lshl_add_u64 v[102:103], v[102:103], 0, s[22:23]
	s_waitcnt vmcnt(13)
	v_lshlrev_b32_e32 v182, 16, v150
	v_and_b32_e32 v183, 0xffff0000, v150
	v_lshlrev_b32_e32 v184, 16, v151
	v_and_b32_e32 v185, 0xffff0000, v151
	v_pk_fma_f32 v[194:195], v[174:175], v[182:183], v[34:35]
	v_pk_fma_f32 v[200:201], v[176:177], v[184:185], v[36:37]
	v_mul_f32_e32 v190, 0x3d372713, v194
	v_mul_f32_e32 v191, 0x3d372713, v195
	v_mul_f32_e32 v192, 0x3d372713, v200
	v_mul_f32_e32 v193, 0x3d372713, v201
	v_mul_f32_e32 v190, v194, v190
	v_mul_f32_e32 v191, v195, v191
	v_mul_f32_e32 v192, v200, v192
	v_mul_f32_e32 v193, v201, v193
	v_fma_f32 v190, v194, v190, v194
	v_fma_f32 v191, v195, v191, v195
	v_fma_f32 v192, v200, v192, v200
	v_fma_f32 v193, v201, v193, v201
	v_mul_f32_e32 v190, 0x3f4c422a, v190
	v_mul_f32_e32 v191, 0x3f4c422a, v191
	v_mul_f32_e32 v192, 0x3f4c422a, v192
	v_mul_f32_e32 v193, 0x3f4c422a, v193
	v_mul_f32_e32 v190, 0xc038aa3b, v190
	v_mul_f32_e32 v191, 0xc038aa3b, v191
	v_mul_f32_e32 v192, 0xc038aa3b, v192
	v_mul_f32_e32 v193, 0xc038aa3b, v193
	v_exp_f32_e32 v190, v190
	v_exp_f32_e32 v191, v191
	v_exp_f32_e32 v192, v192
	v_exp_f32_e32 v193, v193
	v_add_f32_e32 v190, 1.0, v190
	v_add_f32_e32 v191, 1.0, v191
	v_add_f32_e32 v192, 1.0, v192
	v_add_f32_e32 v193, 1.0, v193
	v_rcp_f32_e32 v190, v190
	v_rcp_f32_e32 v191, v191
	v_rcp_f32_e32 v192, v192
	v_rcp_f32_e32 v193, v193
	v_pk_mul_f32 v[194:195], v[194:195], v[190:191]
	v_pk_mul_f32 v[200:201], v[200:201], v[192:193]
	v_cvt_pk_bf16_f32 v196, v194, v195
	v_cvt_pk_bf16_f32 v197, v200, v201
	s_waitcnt vmcnt(12)
	v_lshlrev_b32_e32 v182, 16, v152
	v_and_b32_e32 v183, 0xffff0000, v152
	v_lshlrev_b32_e32 v184, 16, v153
	v_and_b32_e32 v185, 0xffff0000, v153
	v_pk_fma_f32 v[194:195], v[178:179], v[182:183], v[38:39]
	v_pk_fma_f32 v[200:201], v[180:181], v[184:185], v[40:41]
	v_mul_f32_e32 v190, 0x3d372713, v194
	v_mul_f32_e32 v191, 0x3d372713, v195
	v_mul_f32_e32 v192, 0x3d372713, v200
	v_mul_f32_e32 v193, 0x3d372713, v201
	v_mul_f32_e32 v190, v194, v190
	v_mul_f32_e32 v191, v195, v191
	v_mul_f32_e32 v192, v200, v192
	v_mul_f32_e32 v193, v201, v193
	v_fma_f32 v190, v194, v190, v194
	v_fma_f32 v191, v195, v191, v195
	v_fma_f32 v192, v200, v192, v200
	v_fma_f32 v193, v201, v193, v201
	v_mul_f32_e32 v190, 0x3f4c422a, v190
	v_mul_f32_e32 v191, 0x3f4c422a, v191
	v_mul_f32_e32 v192, 0x3f4c422a, v192
	v_mul_f32_e32 v193, 0x3f4c422a, v193
	v_mul_f32_e32 v190, 0xc038aa3b, v190
	v_mul_f32_e32 v191, 0xc038aa3b, v191
	v_mul_f32_e32 v192, 0xc038aa3b, v192
	v_mul_f32_e32 v193, 0xc038aa3b, v193
	v_exp_f32_e32 v190, v190
	v_exp_f32_e32 v191, v191
	v_exp_f32_e32 v192, v192
	v_exp_f32_e32 v193, v193
	v_add_f32_e32 v190, 1.0, v190
	v_add_f32_e32 v191, 1.0, v191
	v_add_f32_e32 v192, 1.0, v192
	v_add_f32_e32 v193, 1.0, v193
	v_rcp_f32_e32 v190, v190
	v_rcp_f32_e32 v191, v191
	v_rcp_f32_e32 v192, v192
	v_rcp_f32_e32 v193, v193
	v_pk_mul_f32 v[194:195], v[194:195], v[190:191]
	v_pk_mul_f32 v[200:201], v[200:201], v[192:193]
	v_cvt_pk_bf16_f32 v198, v194, v195
	v_cvt_pk_bf16_f32 v199, v200, v201
	s_nop 1
	v_permlane32_swap_b32_e32 v196, v198
	v_permlane32_swap_b32_e32 v197, v199
	global_store_dwordx4 v[102:103], v[196:199], off
	s_waitcnt vmcnt(12)
; #define GAS __attribute__((address_space(1)))
; __device__ __forceinline__ unsigned pk2(float lo, float hi) { const f32x2cv v = {lo, hi}; return __builtin_bit_cast(unsigned, __builtin_convertvector(v, bf16x2cv)); }
; __device__ __forceinline__ float gelu_tanh(float x) { const float u = 0.7978845608028654f * (x + 0.044715f * x * x * x); return x * __builtin_amdgcn_rcpf(1.0f + __builtin_amdgcn_exp2f(-2.8853900817779268f * u)); }
; __device__ __forceinline__ void ph_s5_out(Frame& F) {
;     ...
;                 for (int k = 0; k < 4; ++k) { const int tloc = 2 * (wave + 8 * i) + (k >> 1), p0 = 8 * (k & 1) + 4 * hh; const size_t m = (size_t)chunk * 64 + tloc;
;                     const v2u uw = *(const GAS v2u*)((chunk < 256 ? (const bf16*)(ws + WS_UG) : (const bf16*)(ws + WS_UGC)) + ug_index(g, (int)m, p0));
;                     const float y0 = gelu_tanh(acc[i][4 * k] + dsk[p0] * bflo(uw.x)), y1 = gelu_tanh(acc[i][4 * k + 1] + dsk[p0 + 1] * bfhi(uw.x));
;                     const float y2 = gelu_tanh(acc[i][4 * k + 2] + dsk[p0 + 2] * bflo(uw.y)), y3 = gelu_tanh(acc[i][4 * k + 3] + dsk[p0 + 3] * bfhi(uw.y));
;                     v2u zw; zw.x = pk2(y0, y1); zw.y = pk2(y2, y3);
;                     *(GAS v2u*)((bf16*)(ws + WS_Z) + m * 512 + 16 * g + p0) = zw; }
	v_lshlrev_b32_e32 v182, 16, v154
	v_and_b32_e32 v183, 0xffff0000, v154
	v_lshlrev_b32_e32 v184, 16, v155
	v_and_b32_e32 v185, 0xffff0000, v155
	v_pk_fma_f32 v[194:195], v[174:175], v[182:183], v[42:43]
	v_pk_fma_f32 v[200:201], v[176:177], v[184:185], v[44:45]
	v_mul_f32_e32 v190, 0x3d372713, v194
	v_mul_f32_e32 v191, 0x3d372713, v195
	v_mul_f32_e32 v192, 0x3d372713, v200
	v_mul_f32_e32 v193, 0x3d372713, v201
	v_mul_f32_e32 v190, v194, v190
	v_mul_f32_e32 v191, v195, v191
	v_mul_f32_e32 v192, v200, v192
	v_mul_f32_e32 v193, v201, v193
	v_fma_f32 v190, v194, v190, v194
	v_fma_f32 v191, v195, v191, v195
	v_fma_f32 v192, v200, v192, v200
	v_fma_f32 v193, v201, v193, v201
	v_mul_f32_e32 v190, 0x3f4c422a, v190
	v_mul_f32_e32 v191, 0x3f4c422a, v191
	v_mul_f32_e32 v192, 0x3f4c422a, v192
	v_mul_f32_e32 v193, 0x3f4c422a, v193
	v_mul_f32_e32 v190, 0xc038aa3b, v190
	v_mul_f32_e32 v191, 0xc038aa3b, v191
	v_mul_f32_e32 v192, 0xc038aa3b, v192
	v_mul_f32_e32 v193, 0xc038aa3b, v193
	v_exp_f32_e32 v190, v190
	v_exp_f32_e32 v191, v191
	v_exp_f32_e32 v192, v192
	v_exp_f32_e32 v193, v193
	v_add_f32_e32 v190, 1.0, v190
	v_add_f32_e32 v191, 1.0, v191
	v_add_f32_e32 v192, 1.0, v192
	v_add_f32_e32 v193, 1.0, v193
	v_rcp_f32_e32 v190, v190
	v_rcp_f32_e32 v191, v191
	v_rcp_f32_e32 v192, v192
	v_rcp_f32_e32 v193, v193
	v_pk_mul_f32 v[194:195], v[194:195], v[190:191]
	v_pk_mul_f32 v[200:201], v[200:201], v[192:193]
	v_cvt_pk_bf16_f32 v196, v194, v195
	v_cvt_pk_bf16_f32 v197, v200, v201
	s_waitcnt vmcnt(11)
	v_lshlrev_b32_e32 v182, 16, v156
	v_and_b32_e32 v183, 0xffff0000, v156
	v_lshlrev_b32_e32 v184, 16, v157
	v_and_b32_e32 v185, 0xffff0000, v157
	v_pk_fma_f32 v[194:195], v[178:179], v[182:183], v[46:47]
	v_pk_fma_f32 v[200:201], v[180:181], v[184:185], v[48:49]
	v_mul_f32_e32 v190, 0x3d372713, v194
	v_mul_f32_e32 v191, 0x3d372713, v195
	v_mul_f32_e32 v192, 0x3d372713, v200
	v_mul_f32_e32 v193, 0x3d372713, v201
	v_mul_f32_e32 v190, v194, v190
	v_mul_f32_e32 v191, v195, v191
	v_mul_f32_e32 v192, v200, v192
	v_mul_f32_e32 v193, v201, v193
	v_fma_f32 v190, v194, v190, v194
	v_fma_f32 v191, v195, v191, v195
	v_fma_f32 v192, v200, v192, v200
	v_fma_f32 v193, v201, v193, v201
	v_mul_f32_e32 v190, 0x3f4c422a, v190
	v_mul_f32_e32 v191, 0x3f4c422a, v191
	v_mul_f32_e32 v192, 0x3f4c422a, v192
	v_mul_f32_e32 v193, 0x3f4c422a, v193
	v_mul_f32_e32 v190, 0xc038aa3b, v190
	v_mul_f32_e32 v191, 0xc038aa3b, v191
	v_mul_f32_e32 v192, 0xc038aa3b, v192
	v_mul_f32_e32 v193, 0xc038aa3b, v193
	v_exp_f32_e32 v190, v190
	v_exp_f32_e32 v191, v191
	v_exp_f32_e32 v192, v192
	v_exp_f32_e32 v193, v193
	v_add_f32_e32 v190, 1.0, v190
	v_add_f32_e32 v191, 1.0, v191
	v_add_f32_e32 v192, 1.0, v192
	v_add_f32_e32 v193, 1.0, v193
	v_rcp_f32_e32 v190, v190
	v_rcp_f32_e32 v191, v191
	v_rcp_f32_e32 v192, v192
	v_rcp_f32_e32 v193, v193
	v_pk_mul_f32 v[194:195], v[194:195], v[190:191]
	v_pk_mul_f32 v[200:201], v[200:201], v[192:193]
	v_cvt_pk_bf16_f32 v198, v194, v195
	v_cvt_pk_bf16_f32 v199, v200, v201
	s_nop 1
	v_permlane32_swap_b32_e32 v196, v198
	v_permlane32_swap_b32_e32 v197, v199
	global_store_dwordx4 v[102:103], v[196:199], off offset:1024
	v_lshl_add_u64 v[102:103], v[102:103], 0, s[22:23]
	s_waitcnt vmcnt(11)
	v_lshlrev_b32_e32 v182, 16, v158
	v_and_b32_e32 v183, 0xffff0000, v158
	v_lshlrev_b32_e32 v184, 16, v159
	v_and_b32_e32 v185, 0xffff0000, v159
	v_pk_fma_f32 v[194:195], v[174:175], v[182:183], v[18:19]
	v_pk_fma_f32 v[200:201], v[176:177], v[184:185], v[20:21]
	v_mul_f32_e32 v190, 0x3d372713, v194
	v_mul_f32_e32 v191, 0x3d372713, v195
	v_mul_f32_e32 v192, 0x3d372713, v200
	v_mul_f32_e32 v193, 0x3d372713, v201
	v_mul_f32_e32 v190, v194, v190
	v_mul_f32_e32 v191, v195, v191
	v_mul_f32_e32 v192, v200, v192
	v_mul_f32_e32 v193, v201, v193
	v_fma_f32 v190, v194, v190, v194
	v_fma_f32 v191, v195, v191, v195
	v_fma_f32 v192, v200, v192, v200
	v_fma_f32 v193, v201, v193, v201
	v_mul_f32_e32 v190, 0x3f4c422a, v190
	v_mul_f32_e32 v191, 0x3f4c422a, v191
	v_mul_f32_e32 v192, 0x3f4c422a, v192
	v_mul_f32_e32 v193, 0x3f4c422a, v193
	v_mul_f32_e32 v190, 0xc038aa3b, v190
	v_mul_f32_e32 v191, 0xc038aa3b, v191
	v_mul_f32_e32 v192, 0xc038aa3b, v192
	v_mul_f32_e32 v193, 0xc038aa3b, v193
	v_exp_f32_e32 v190, v190
	v_exp_f32_e32 v191, v191
	v_exp_f32_e32 v192, v192
	v_exp_f32_e32 v193, v193
	v_add_f32_e32 v190, 1.0, v190
	v_add_f32_e32 v191, 1.0, v191
	v_add_f32_e32 v192, 1.0, v192
	v_add_f32_e32 v193, 1.0, v193
	v_rcp_f32_e32 v190, v190
	v_rcp_f32_e32 v191, v191
	v_rcp_f32_e32 v192, v192
	v_rcp_f32_e32 v193, v193
	v_pk_mul_f32 v[194:195], v[194:195], v[190:191]
	v_pk_mul_f32 v[200:201], v[200:201], v[192:193]
	v_cvt_pk_bf16_f32 v196, v194, v195
	v_cvt_pk_bf16_f32 v197, v200, v201
	s_waitcnt vmcnt(10)
	v_lshlrev_b32_e32 v182, 16, v160
	v_and_b32_e32 v183, 0xffff0000, v160
	v_lshlrev_b32_e32 v184, 16, v161
	v_and_b32_e32 v185, 0xffff0000, v161
	v_pk_fma_f32 v[194:195], v[178:179], v[182:183], v[22:23]
	v_pk_fma_f32 v[200:201], v[180:181], v[184:185], v[24:25]
	v_mul_f32_e32 v190, 0x3d372713, v194
	v_mul_f32_e32 v191, 0x3d372713, v195
	v_mul_f32_e32 v192, 0x3d372713, v200
	v_mul_f32_e32 v193, 0x3d372713, v201
	v_mul_f32_e32 v190, v194, v190
	v_mul_f32_e32 v191, v195, v191
	v_mul_f32_e32 v192, v200, v192
	v_mul_f32_e32 v193, v201, v193
	v_fma_f32 v190, v194, v190, v194
	v_fma_f32 v191, v195, v191, v195
	v_fma_f32 v192, v200, v192, v200
	v_fma_f32 v193, v201, v193, v201
	v_mul_f32_e32 v190, 0x3f4c422a, v190
	v_mul_f32_e32 v191, 0x3f4c422a, v191
	v_mul_f32_e32 v192, 0x3f4c422a, v192
	v_mul_f32_e32 v193, 0x3f4c422a, v193
	v_mul_f32_e32 v190, 0xc038aa3b, v190
	v_mul_f32_e32 v191, 0xc038aa3b, v191
	v_mul_f32_e32 v192, 0xc038aa3b, v192
	v_mul_f32_e32 v193, 0xc038aa3b, v193
	v_exp_f32_e32 v190, v190
	v_exp_f32_e32 v191, v191
	v_exp_f32_e32 v192, v192
	v_exp_f32_e32 v193, v193
	v_add_f32_e32 v190, 1.0, v190
	v_add_f32_e32 v191, 1.0, v191
	v_add_f32_e32 v192, 1.0, v192
	v_add_f32_e32 v193, 1.0, v193
	v_rcp_f32_e32 v190, v190
	v_rcp_f32_e32 v191, v191
	v_rcp_f32_e32 v192, v192
	v_rcp_f32_e32 v193, v193
	v_pk_mul_f32 v[194:195], v[194:195], v[190:191]
	v_pk_mul_f32 v[200:201], v[200:201], v[192:193]
	v_cvt_pk_bf16_f32 v198, v194, v195
	v_cvt_pk_bf16_f32 v199, v200, v201
	s_nop 1
	v_permlane32_swap_b32_e32 v196, v198
	v_permlane32_swap_b32_e32 v197, v199
	global_store_dwordx4 v[102:103], v[196:199], off
	s_waitcnt vmcnt(10)
; #define GAS __attribute__((address_space(1)))
; __device__ __forceinline__ unsigned pk2(float lo, float hi) { const f32x2cv v = {lo, hi}; return __builtin_bit_cast(unsigned, __builtin_convertvector(v, bf16x2cv)); }
; __device__ __forceinline__ float gelu_tanh(float x) { const float u = 0.7978845608028654f * (x + 0.044715f * x * x * x); return x * __builtin_amdgcn_rcpf(1.0f + __builtin_amdgcn_exp2f(-2.8853900817779268f * u)); }
; __device__ __forceinline__ void ph_s5_out(Frame& F) {
;     ...
;                 for (int k = 0; k < 4; ++k) { const int tloc = 2 * (wave + 8 * i) + (k >> 1), p0 = 8 * (k & 1) + 4 * hh; const size_t m = (size_t)chunk * 64 + tloc;
;                     const v2u uw = *(const GAS v2u*)((chunk < 256 ? (const bf16*)(ws + WS_UG) : (const bf16*)(ws + WS_UGC)) + ug_index(g, (int)m, p0));
;                     const float y0 = gelu_tanh(acc[i][4 * k] + dsk[p0] * bflo(uw.x)), y1 = gelu_tanh(acc[i][4 * k + 1] + dsk[p0 + 1] * bfhi(uw.x));
;                     const float y2 = gelu_tanh(acc[i][4 * k + 2] + dsk[p0 + 2] * bflo(uw.y)), y3 = gelu_tanh(acc[i][4 * k + 3] + dsk[p0 + 3] * bfhi(uw.y));
;                     v2u zw; zw.x = pk2(y0, y1); zw.y = pk2(y2, y3);
;                     *(GAS v2u*)((bf16*)(ws + WS_Z) + m * 512 + 16 * g + p0) = zw; }
	v_lshlrev_b32_e32 v182, 16, v162
	v_and_b32_e32 v183, 0xffff0000, v162
	v_lshlrev_b32_e32 v184, 16, v163
	v_and_b32_e32 v185, 0xffff0000, v163
	v_pk_fma_f32 v[194:195], v[174:175], v[182:183], v[26:27]
	v_pk_fma_f32 v[200:201], v[176:177], v[184:185], v[28:29]
	v_mul_f32_e32 v190, 0x3d372713, v194
	v_mul_f32_e32 v191, 0x3d372713, v195
	v_mul_f32_e32 v192, 0x3d372713, v200
	v_mul_f32_e32 v193, 0x3d372713, v201
	v_mul_f32_e32 v190, v194, v190
	v_mul_f32_e32 v191, v195, v191
	v_mul_f32_e32 v192, v200, v192
	v_mul_f32_e32 v193, v201, v193
	v_fma_f32 v190, v194, v190, v194
	v_fma_f32 v191, v195, v191, v195
	v_fma_f32 v192, v200, v192, v200
	v_fma_f32 v193, v201, v193, v201
	v_mul_f32_e32 v190, 0x3f4c422a, v190
	v_mul_f32_e32 v191, 0x3f4c422a, v191
	v_mul_f32_e32 v192, 0x3f4c422a, v192
	v_mul_f32_e32 v193, 0x3f4c422a, v193
	v_mul_f32_e32 v190, 0xc038aa3b, v190
	v_mul_f32_e32 v191, 0xc038aa3b, v191
	v_mul_f32_e32 v192, 0xc038aa3b, v192
	v_mul_f32_e32 v193, 0xc038aa3b, v193
	v_exp_f32_e32 v190, v190
	v_exp_f32_e32 v191, v191
	v_exp_f32_e32 v192, v192
	v_exp_f32_e32 v193, v193
	v_add_f32_e32 v190, 1.0, v190
	v_add_f32_e32 v191, 1.0, v191
	v_add_f32_e32 v192, 1.0, v192
	v_add_f32_e32 v193, 1.0, v193
	v_rcp_f32_e32 v190, v190
	v_rcp_f32_e32 v191, v191
	v_rcp_f32_e32 v192, v192
	v_rcp_f32_e32 v193, v193
	v_pk_mul_f32 v[194:195], v[194:195], v[190:191]
	v_pk_mul_f32 v[200:201], v[200:201], v[192:193]
	v_cvt_pk_bf16_f32 v196, v194, v195
	v_cvt_pk_bf16_f32 v197, v200, v201
	s_waitcnt vmcnt(9)
	v_lshlrev_b32_e32 v182, 16, v164
	v_and_b32_e32 v183, 0xffff0000, v164
	v_lshlrev_b32_e32 v184, 16, v165
	v_and_b32_e32 v185, 0xffff0000, v165
	v_pk_fma_f32 v[194:195], v[178:179], v[182:183], v[30:31]
	v_pk_fma_f32 v[200:201], v[180:181], v[184:185], v[32:33]
	v_mul_f32_e32 v190, 0x3d372713, v194
	v_mul_f32_e32 v191, 0x3d372713, v195
	v_mul_f32_e32 v192, 0x3d372713, v200
	v_mul_f32_e32 v193, 0x3d372713, v201
	v_mul_f32_e32 v190, v194, v190
	v_mul_f32_e32 v191, v195, v191
	v_mul_f32_e32 v192, v200, v192
	v_mul_f32_e32 v193, v201, v193
	v_fma_f32 v190, v194, v190, v194
	v_fma_f32 v191, v195, v191, v195
	v_fma_f32 v192, v200, v192, v200
	v_fma_f32 v193, v201, v193, v201
	v_mul_f32_e32 v190, 0x3f4c422a, v190
	v_mul_f32_e32 v191, 0x3f4c422a, v191
	v_mul_f32_e32 v192, 0x3f4c422a, v192
	v_mul_f32_e32 v193, 0x3f4c422a, v193
	v_mul_f32_e32 v190, 0xc038aa3b, v190
	v_mul_f32_e32 v191, 0xc038aa3b, v191
	v_mul_f32_e32 v192, 0xc038aa3b, v192
	v_mul_f32_e32 v193, 0xc038aa3b, v193
	v_exp_f32_e32 v190, v190
	v_exp_f32_e32 v191, v191
	v_exp_f32_e32 v192, v192
	v_exp_f32_e32 v193, v193
	v_add_f32_e32 v190, 1.0, v190
	v_add_f32_e32 v191, 1.0, v191
	v_add_f32_e32 v192, 1.0, v192
	v_add_f32_e32 v193, 1.0, v193
	v_rcp_f32_e32 v190, v190
	v_rcp_f32_e32 v191, v191
	v_rcp_f32_e32 v192, v192
	v_rcp_f32_e32 v193, v193
	v_pk_mul_f32 v[194:195], v[194:195], v[190:191]
	v_pk_mul_f32 v[200:201], v[200:201], v[192:193]
	v_cvt_pk_bf16_f32 v198, v194, v195
	v_cvt_pk_bf16_f32 v199, v200, v201
	s_nop 1
	v_permlane32_swap_b32_e32 v196, v198
	v_permlane32_swap_b32_e32 v197, v199
	global_store_dwordx4 v[102:103], v[196:199], off offset:1024
	v_lshl_add_u64 v[102:103], v[102:103], 0, s[22:23]
	s_waitcnt vmcnt(9)
	v_lshlrev_b32_e32 v182, 16, v166
	v_and_b32_e32 v183, 0xffff0000, v166
	v_lshlrev_b32_e32 v184, 16, v167
	v_and_b32_e32 v185, 0xffff0000, v167
	v_pk_fma_f32 v[194:195], v[174:175], v[182:183], v[2:3]
	v_pk_fma_f32 v[200:201], v[176:177], v[184:185], v[4:5]
	v_mul_f32_e32 v190, 0x3d372713, v194
	v_mul_f32_e32 v191, 0x3d372713, v195
	v_mul_f32_e32 v192, 0x3d372713, v200
	v_mul_f32_e32 v193, 0x3d372713, v201
	v_mul_f32_e32 v190, v194, v190
	v_mul_f32_e32 v191, v195, v191
	v_mul_f32_e32 v192, v200, v192
	v_mul_f32_e32 v193, v201, v193
	v_fma_f32 v190, v194, v190, v194
	v_fma_f32 v191, v195, v191, v195
	v_fma_f32 v192, v200, v192, v200
	v_fma_f32 v193, v201, v193, v201
	v_mul_f32_e32 v190, 0x3f4c422a, v190
	v_mul_f32_e32 v191, 0x3f4c422a, v191
	v_mul_f32_e32 v192, 0x3f4c422a, v192
	v_mul_f32_e32 v193, 0x3f4c422a, v193
	v_mul_f32_e32 v190, 0xc038aa3b, v190
	v_mul_f32_e32 v191, 0xc038aa3b, v191
	v_mul_f32_e32 v192, 0xc038aa3b, v192
	v_mul_f32_e32 v193, 0xc038aa3b, v193
	v_exp_f32_e32 v190, v190
	v_exp_f32_e32 v191, v191
	v_exp_f32_e32 v192, v192
	v_exp_f32_e32 v193, v193
	v_add_f32_e32 v190, 1.0, v190
	v_add_f32_e32 v191, 1.0, v191
	v_add_f32_e32 v192, 1.0, v192
	v_add_f32_e32 v193, 1.0, v193
	v_rcp_f32_e32 v190, v190
	v_rcp_f32_e32 v191, v191
	v_rcp_f32_e32 v192, v192
	v_rcp_f32_e32 v193, v193
	v_pk_mul_f32 v[194:195], v[194:195], v[190:191]
	v_pk_mul_f32 v[200:201], v[200:201], v[192:193]
	v_cvt_pk_bf16_f32 v196, v194, v195
	v_cvt_pk_bf16_f32 v197, v200, v201
	s_waitcnt vmcnt(8)
; #define GAS __attribute__((address_space(1)))
; __device__ __forceinline__ unsigned pk2(float lo, float hi) { const f32x2cv v = {lo, hi}; return __builtin_bit_cast(unsigned, __builtin_convertvector(v, bf16x2cv)); }
; __device__ __forceinline__ float gelu_tanh(float x) { const float u = 0.7978845608028654f * (x + 0.044715f * x * x * x); return x * __builtin_amdgcn_rcpf(1.0f + __builtin_amdgcn_exp2f(-2.8853900817779268f * u)); }
; __device__ __forceinline__ void ph_s5_out(Frame& F) {
;     ...
;                 for (int k = 0; k < 4; ++k) { const int tloc = 2 * (wave + 8 * i) + (k >> 1), p0 = 8 * (k & 1) + 4 * hh; const size_t m = (size_t)chunk * 64 + tloc;
;                     const v2u uw = *(const GAS v2u*)((chunk < 256 ? (const bf16*)(ws + WS_UG) : (const bf16*)(ws + WS_UGC)) + ug_index(g, (int)m, p0));
;                     const float y0 = gelu_tanh(acc[i][4 * k] + dsk[p0] * bflo(uw.x)), y1 = gelu_tanh(acc[i][4 * k + 1] + dsk[p0 + 1] * bfhi(uw.x));
;                     const float y2 = gelu_tanh(acc[i][4 * k + 2] + dsk[p0 + 2] * bflo(uw.y)), y3 = gelu_tanh(acc[i][4 * k + 3] + dsk[p0 + 3] * bfhi(uw.y));
;                     v2u zw; zw.x = pk2(y0, y1); zw.y = pk2(y2, y3);
;                     *(GAS v2u*)((bf16*)(ws + WS_Z) + m * 512 + 16 * g + p0) = zw; }
	v_lshlrev_b32_e32 v182, 16, v168
	v_and_b32_e32 v183, 0xffff0000, v168
	v_lshlrev_b32_e32 v184, 16, v169
	v_and_b32_e32 v185, 0xffff0000, v169
	v_pk_fma_f32 v[194:195], v[178:179], v[182:183], v[6:7]
	v_pk_fma_f32 v[200:201], v[180:181], v[184:185], v[8:9]
	v_mul_f32_e32 v190, 0x3d372713, v194
	v_mul_f32_e32 v191, 0x3d372713, v195
	v_mul_f32_e32 v192, 0x3d372713, v200
	v_mul_f32_e32 v193, 0x3d372713, v201
	v_mul_f32_e32 v190, v194, v190
	v_mul_f32_e32 v191, v195, v191
	v_mul_f32_e32 v192, v200, v192
	v_mul_f32_e32 v193, v201, v193
	v_fma_f32 v190, v194, v190, v194
	v_fma_f32 v191, v195, v191, v195
	v_fma_f32 v192, v200, v192, v200
	v_fma_f32 v193, v201, v193, v201
	v_mul_f32_e32 v190, 0x3f4c422a, v190
	v_mul_f32_e32 v191, 0x3f4c422a, v191
	v_mul_f32_e32 v192, 0x3f4c422a, v192
	v_mul_f32_e32 v193, 0x3f4c422a, v193
	v_mul_f32_e32 v190, 0xc038aa3b, v190
	v_mul_f32_e32 v191, 0xc038aa3b, v191
	v_mul_f32_e32 v192, 0xc038aa3b, v192
	v_mul_f32_e32 v193, 0xc038aa3b, v193
	v_exp_f32_e32 v190, v190
	v_exp_f32_e32 v191, v191
	v_exp_f32_e32 v192, v192
	v_exp_f32_e32 v193, v193
	v_add_f32_e32 v190, 1.0, v190
	v_add_f32_e32 v191, 1.0, v191
	v_add_f32_e32 v192, 1.0, v192
	v_add_f32_e32 v193, 1.0, v193
	v_rcp_f32_e32 v190, v190
	v_rcp_f32_e32 v191, v191
	v_rcp_f32_e32 v192, v192
	v_rcp_f32_e32 v193, v193
	v_pk_mul_f32 v[194:195], v[194:195], v[190:191]
	v_pk_mul_f32 v[200:201], v[200:201], v[192:193]
	v_cvt_pk_bf16_f32 v198, v194, v195
	v_cvt_pk_bf16_f32 v199, v200, v201
	s_nop 1
	v_permlane32_swap_b32_e32 v196, v198
	v_permlane32_swap_b32_e32 v197, v199
	global_store_dwordx4 v[102:103], v[196:199], off
	s_waitcnt vmcnt(8)
	v_lshlrev_b32_e32 v182, 16, v170
	v_and_b32_e32 v183, 0xffff0000, v170
	v_lshlrev_b32_e32 v184, 16, v171
	v_and_b32_e32 v185, 0xffff0000, v171
	v_pk_fma_f32 v[194:195], v[174:175], v[182:183], v[10:11]
	v_pk_fma_f32 v[200:201], v[176:177], v[184:185], v[12:13]
	v_mul_f32_e32 v190, 0x3d372713, v194
	v_mul_f32_e32 v191, 0x3d372713, v195
	v_mul_f32_e32 v192, 0x3d372713, v200
	v_mul_f32_e32 v193, 0x3d372713, v201
	v_mul_f32_e32 v190, v194, v190
	v_mul_f32_e32 v191, v195, v191
	v_mul_f32_e32 v192, v200, v192
	v_mul_f32_e32 v193, v201, v193
	v_fma_f32 v190, v194, v190, v194
	v_fma_f32 v191, v195, v191, v195
	v_fma_f32 v192, v200, v192, v200
	v_fma_f32 v193, v201, v193, v201
	v_mul_f32_e32 v190, 0x3f4c422a, v190
	v_mul_f32_e32 v191, 0x3f4c422a, v191
	v_mul_f32_e32 v192, 0x3f4c422a, v192
	v_mul_f32_e32 v193, 0x3f4c422a, v193
	v_mul_f32_e32 v190, 0xc038aa3b, v190
	v_mul_f32_e32 v191, 0xc038aa3b, v191
	v_mul_f32_e32 v192, 0xc038aa3b, v192
	v_mul_f32_e32 v193, 0xc038aa3b, v193
	v_exp_f32_e32 v190, v190
	v_exp_f32_e32 v191, v191
	v_exp_f32_e32 v192, v192
	v_exp_f32_e32 v193, v193
	v_add_f32_e32 v190, 1.0, v190
	v_add_f32_e32 v191, 1.0, v191
	v_add_f32_e32 v192, 1.0, v192
	v_add_f32_e32 v193, 1.0, v193
	v_rcp_f32_e32 v190, v190
	v_rcp_f32_e32 v191, v191
	v_rcp_f32_e32 v192, v192
	v_rcp_f32_e32 v193, v193
	v_pk_mul_f32 v[194:195], v[194:195], v[190:191]
	v_pk_mul_f32 v[200:201], v[200:201], v[192:193]
	v_cvt_pk_bf16_f32 v196, v194, v195
	v_cvt_pk_bf16_f32 v197, v200, v201
	s_waitcnt vmcnt(7)
	v_lshlrev_b32_e32 v182, 16, v172
	v_and_b32_e32 v183, 0xffff0000, v172
	v_lshlrev_b32_e32 v184, 16, v173
	v_and_b32_e32 v185, 0xffff0000, v173
	v_pk_fma_f32 v[194:195], v[178:179], v[182:183], v[14:15]
	v_pk_fma_f32 v[200:201], v[180:181], v[184:185], v[16:17]
	v_mul_f32_e32 v190, 0x3d372713, v194
	v_mul_f32_e32 v191, 0x3d372713, v195
	v_mul_f32_e32 v192, 0x3d372713, v200
	v_mul_f32_e32 v193, 0x3d372713, v201
	v_mul_f32_e32 v190, v194, v190
	v_mul_f32_e32 v191, v195, v191
	v_mul_f32_e32 v192, v200, v192
	v_mul_f32_e32 v193, v201, v193
	v_fma_f32 v190, v194, v190, v194
	v_fma_f32 v191, v195, v191, v195
	v_fma_f32 v192, v200, v192, v200
	v_fma_f32 v193, v201, v193, v201
	v_mul_f32_e32 v190, 0x3f4c422a, v190
	v_mul_f32_e32 v191, 0x3f4c422a, v191
	v_mul_f32_e32 v192, 0x3f4c422a, v192
	v_mul_f32_e32 v193, 0x3f4c422a, v193
	v_mul_f32_e32 v190, 0xc038aa3b, v190
	v_mul_f32_e32 v191, 0xc038aa3b, v191
	v_mul_f32_e32 v192, 0xc038aa3b, v192
	v_mul_f32_e32 v193, 0xc038aa3b, v193
	v_exp_f32_e32 v190, v190
	v_exp_f32_e32 v191, v191
	v_exp_f32_e32 v192, v192
	v_exp_f32_e32 v193, v193
	v_add_f32_e32 v190, 1.0, v190
	v_add_f32_e32 v191, 1.0, v191
	v_add_f32_e32 v192, 1.0, v192
	v_add_f32_e32 v193, 1.0, v193
	v_rcp_f32_e32 v190, v190
	v_rcp_f32_e32 v191, v191
	v_rcp_f32_e32 v192, v192
	v_rcp_f32_e32 v193, v193
	v_pk_mul_f32 v[194:195], v[194:195], v[190:191]
	v_pk_mul_f32 v[200:201], v[200:201], v[192:193]
	v_cvt_pk_bf16_f32 v198, v194, v195
	v_cvt_pk_bf16_f32 v199, v200, v201
	s_nop 1
	v_permlane32_swap_b32_e32 v196, v198
	v_permlane32_swap_b32_e32 v197, v199
	global_store_dwordx4 v[102:103], v[196:199], off offset:1024
	s_branch .LBB0_963
